# chunk_prep forward substitution rewritten: 8 waves, lane halves split the dot product, A broadcast by DPP row_newbcast
# speedup vs baseline: 1.0628x; 1.0094x over previous
; #define LAS __attribute__((address_space(3)))
; __device__ __forceinline__ void phase_chunk_prep(const Params& p, LAS unsigned char* lds, int wave_s) {
;     ...
;         if (tid < 256) {
;             const int col = tid; float sol[64];
; #pragma unroll
;             for (int i = 0; i < 64; ++i) sol[i] = 0.f;
; #pragma unroll
;             for (int i = 0; i < 64; ++i) {
;                 float s0 = RHS[i * 256 + col], s1 = 0.f, s2 = 0.f, s3 = 0.f;
; #pragma unroll
;                 for (int j4 = 0; j4 < (i + 3) / 4; ++j4) { const f32x4 a = *(const LAS f32x4*)(AM + i * 64 + 4 * j4);
;                     s0 -= a.x * sol[4 * j4]; s1 -= a.y * sol[4 * j4 + 1]; s2 -= a.z * sol[4 * j4 + 2]; s3 -= a.w * sol[4 * j4 + 3]; }
;                 sol[i] = (s0 + s1) + (s2 + s3);
;             }
.Lcpstage_n_end:
	s_lshr_b32 s84, s24, 6
	v_mbcnt_lo_u32_b32 v32, -1, 0
	v_mbcnt_hi_u32_b32 v32, -1, v32
	v_and_b32_e32 v33, 31, v32
	v_lshrrev_b32_e32 v34, 5, v32
	s_lshl_b32 s85, s84, 5
	v_add_u32_e32 v35, s85, v33
	v_and_b32_e32 v36, 15, v32
	v_lshrrev_b32_e32 v37, 1, v36
	v_lshlrev_b32_e32 v37, 4, v37
	v_and_b32_e32 v38, 1, v36
	v_lshlrev_b32_e32 v38, 2, v38
	v_lshl_add_u32 v37, v34, 3, v37
	v_add_u32_e32 v37, v37, v38
	v_add_u32_e32 v37, 0x8800, v37
	v_lshlrev_b32_e32 v38, 2, v35
	v_add_u32_e32 v38, 0xc800, v38
	v_cmp_eq_u32_e32 vcc, 0, v34
	s_nop 1
	v_cndmask_b32_e64 v39, 0, 1.0, vcc
	v_mov_b32_e32 v0, 0
	v_mov_b32_e32 v1, 0
	v_mov_b32_e32 v2, 0
	v_mov_b32_e32 v3, 0
	v_mov_b32_e32 v4, 0
	v_mov_b32_e32 v5, 0
	v_mov_b32_e32 v6, 0
	v_mov_b32_e32 v7, 0
	v_mov_b32_e32 v8, 0
	v_mov_b32_e32 v9, 0
	v_mov_b32_e32 v10, 0
	v_mov_b32_e32 v11, 0
	v_mov_b32_e32 v12, 0
	v_mov_b32_e32 v13, 0
	v_mov_b32_e32 v14, 0
	v_mov_b32_e32 v15, 0
	v_mov_b32_e32 v16, 0
	v_mov_b32_e32 v17, 0
	v_mov_b32_e32 v18, 0
	v_mov_b32_e32 v19, 0
	v_mov_b32_e32 v20, 0
	v_mov_b32_e32 v21, 0
	v_mov_b32_e32 v22, 0
	v_mov_b32_e32 v23, 0
	v_mov_b32_e32 v24, 0
	v_mov_b32_e32 v25, 0
	v_mov_b32_e32 v26, 0
	v_mov_b32_e32 v27, 0
	v_mov_b32_e32 v28, 0
	v_mov_b32_e32 v29, 0
	v_mov_b32_e32 v30, 0
	v_mov_b32_e32 v31, 0
	ds_read_b32 v56, v38
	ds_read_b32 v48, v37
	ds_read_b32 v57, v38 offset:1024
	ds_read_b32 v50, v37 offset:256
	ds_read_b32 v58, v38 offset:2048
	ds_read_b32 v52, v37 offset:512
	ds_read_b32 v59, v38 offset:3072
	ds_read_b32 v54, v37 offset:768
	s_waitcnt lgkmcnt(6)
	v_mul_f32_e32 v40, v56, v39
	v_mov_b32_e32 v41, 0
	ds_read_b32 v56, v38 offset:4096
	ds_read_b32 v48, v37 offset:1024
	v_add_f32_e32 v42, v40, v41
	v_mov_b32_e32 v43, v42
	s_nop 1
	v_permlane32_swap_b32_e32 v42, v43
	s_nop 1
	v_add_f32_dpp v0, v42, v43 quad_perm:[0,1,2,3] row_mask:0x3 bank_mask:0xf
	s_waitcnt lgkmcnt(6)
	v_mul_f32_e32 v40, v57, v39
	v_mov_b32_e32 v41, 0
	v_fmac_f32_dpp v40, -v50, v0 row_newbcast:0 row_mask:0xf bank_mask:0xf
	ds_read_b32 v57, v38 offset:5120
	ds_read_b32 v50, v37 offset:1280
	v_add_f32_e32 v42, v40, v41
	v_mov_b32_e32 v43, v42
	s_nop 1
	v_permlane32_swap_b32_e32 v42, v43
	s_nop 1
	v_add_f32_dpp v1, v42, v43 quad_perm:[0,1,2,3] row_mask:0x3 bank_mask:0xf
	s_waitcnt lgkmcnt(6)
	v_mul_f32_e32 v40, v58, v39
	v_mov_b32_e32 v41, 0
	v_fmac_f32_dpp v40, -v52, v0 row_newbcast:0 row_mask:0xf bank_mask:0xf
	v_fmac_f32_dpp v41, -v52, v1 row_newbcast:1 row_mask:0xf bank_mask:0xf
	ds_read_b32 v58, v38 offset:6144
	ds_read_b32 v52, v37 offset:1536
	v_add_f32_e32 v42, v40, v41
	v_mov_b32_e32 v43, v42
	s_nop 1
	v_permlane32_swap_b32_e32 v42, v43
	s_nop 1
	v_add_f32_dpp v0, v42, v43 quad_perm:[0,1,2,3] row_mask:0xc bank_mask:0xf
	s_waitcnt lgkmcnt(6)
	v_mul_f32_e32 v40, v59, v39
	v_mov_b32_e32 v41, 0
	v_fmac_f32_dpp v40, -v54, v0 row_newbcast:0 row_mask:0xf bank_mask:0xf
	v_fmac_f32_dpp v41, -v54, v1 row_newbcast:1 row_mask:0xf bank_mask:0xf
	ds_read_b32 v59, v38 offset:7168
	ds_read_b32 v54, v37 offset:1792
	v_add_f32_e32 v42, v40, v41
	v_mov_b32_e32 v43, v42
	s_nop 1
	v_permlane32_swap_b32_e32 v42, v43
	s_nop 1
	v_add_f32_dpp v1, v42, v43 quad_perm:[0,1,2,3] row_mask:0xc bank_mask:0xf
	s_waitcnt lgkmcnt(6)
	v_mul_f32_e32 v40, v56, v39
	v_mov_b32_e32 v41, 0
	v_fmac_f32_dpp v40, -v48, v0 row_newbcast:0 row_mask:0xf bank_mask:0xf
	v_fmac_f32_dpp v41, -v48, v1 row_newbcast:1 row_mask:0xf bank_mask:0xf
	ds_read_b32 v56, v38 offset:8192
	ds_read_b32 v48, v37 offset:2048
	v_add_f32_e32 v42, v40, v41
	v_mov_b32_e32 v43, v42
	s_nop 1
	v_permlane32_swap_b32_e32 v42, v43
	s_nop 1
	v_add_f32_dpp v2, v42, v43 quad_perm:[0,1,2,3] row_mask:0x3 bank_mask:0xf
	s_waitcnt lgkmcnt(6)
	v_mul_f32_e32 v40, v57, v39
	v_mov_b32_e32 v41, 0
	v_fmac_f32_dpp v40, -v50, v0 row_newbcast:0 row_mask:0xf bank_mask:0xf
	v_fmac_f32_dpp v41, -v50, v1 row_newbcast:1 row_mask:0xf bank_mask:0xf
	v_fmac_f32_dpp v40, -v50, v2 row_newbcast:2 row_mask:0xf bank_mask:0xf
	ds_read_b32 v57, v38 offset:9216
	ds_read_b32 v50, v37 offset:2304
	v_add_f32_e32 v42, v40, v41
	v_mov_b32_e32 v43, v42
	s_nop 1
	v_permlane32_swap_b32_e32 v42, v43
	s_nop 1
	v_add_f32_dpp v3, v42, v43 quad_perm:[0,1,2,3] row_mask:0x3 bank_mask:0xf
	s_waitcnt lgkmcnt(6)
	v_mul_f32_e32 v40, v58, v39
	v_mov_b32_e32 v41, 0
	v_fmac_f32_dpp v40, -v52, v0 row_newbcast:0 row_mask:0xf bank_mask:0xf
	v_fmac_f32_dpp v41, -v52, v1 row_newbcast:1 row_mask:0xf bank_mask:0xf
	v_fmac_f32_dpp v40, -v52, v2 row_newbcast:2 row_mask:0xf bank_mask:0xf
	v_fmac_f32_dpp v41, -v52, v3 row_newbcast:3 row_mask:0xf bank_mask:0xf
	ds_read_b32 v58, v38 offset:10240
	ds_read_b32 v52, v37 offset:2560
	v_add_f32_e32 v42, v40, v41
	v_mov_b32_e32 v43, v42
	s_nop 1
	v_permlane32_swap_b32_e32 v42, v43
	s_nop 1
	v_add_f32_dpp v2, v42, v43 quad_perm:[0,1,2,3] row_mask:0xc bank_mask:0xf
	s_waitcnt lgkmcnt(6)
	v_mul_f32_e32 v40, v59, v39
	v_mov_b32_e32 v41, 0
	v_fmac_f32_dpp v40, -v54, v0 row_newbcast:0 row_mask:0xf bank_mask:0xf
	v_fmac_f32_dpp v41, -v54, v1 row_newbcast:1 row_mask:0xf bank_mask:0xf
	v_fmac_f32_dpp v40, -v54, v2 row_newbcast:2 row_mask:0xf bank_mask:0xf
	v_fmac_f32_dpp v41, -v54, v3 row_newbcast:3 row_mask:0xf bank_mask:0xf
	ds_read_b32 v59, v38 offset:11264
	ds_read_b32 v54, v37 offset:2816
	v_add_f32_e32 v42, v40, v41
	v_mov_b32_e32 v43, v42
	s_nop 1
	v_permlane32_swap_b32_e32 v42, v43
	s_nop 1
	v_add_f32_dpp v3, v42, v43 quad_perm:[0,1,2,3] row_mask:0xc bank_mask:0xf
	s_waitcnt lgkmcnt(6)
; #define LAS __attribute__((address_space(3)))
; __device__ __forceinline__ void phase_chunk_prep(const Params& p, LAS unsigned char* lds, int wave_s) {
;     ...
;             for (int i = 0; i < 64; ++i) {
;                 float s0 = RHS[i * 256 + col], s1 = 0.f, s2 = 0.f, s3 = 0.f;
; #pragma unroll
;                 for (int j4 = 0; j4 < (i + 3) / 4; ++j4) { const f32x4 a = *(const LAS f32x4*)(AM + i * 64 + 4 * j4);
;                     s0 -= a.x * sol[4 * j4]; s1 -= a.y * sol[4 * j4 + 1]; s2 -= a.z * sol[4 * j4 + 2]; s3 -= a.w * sol[4 * j4 + 3]; }
;                 sol[i] = (s0 + s1) + (s2 + s3);
;             }
	v_mul_f32_e32 v40, v56, v39
	v_mov_b32_e32 v41, 0
	v_fmac_f32_dpp v40, -v48, v0 row_newbcast:0 row_mask:0xf bank_mask:0xf
	v_fmac_f32_dpp v41, -v48, v1 row_newbcast:1 row_mask:0xf bank_mask:0xf
	v_fmac_f32_dpp v40, -v48, v2 row_newbcast:2 row_mask:0xf bank_mask:0xf
	v_fmac_f32_dpp v41, -v48, v3 row_newbcast:3 row_mask:0xf bank_mask:0xf
	ds_read_b32 v56, v38 offset:12288
	ds_read_b32 v48, v37 offset:3072
	v_add_f32_e32 v42, v40, v41
	v_mov_b32_e32 v43, v42
	s_nop 1
	v_permlane32_swap_b32_e32 v42, v43
	s_nop 1
	v_add_f32_dpp v4, v42, v43 quad_perm:[0,1,2,3] row_mask:0x3 bank_mask:0xf
	s_waitcnt lgkmcnt(6)
	v_mul_f32_e32 v40, v57, v39
	v_mov_b32_e32 v41, 0
	v_fmac_f32_dpp v40, -v50, v0 row_newbcast:0 row_mask:0xf bank_mask:0xf
	v_fmac_f32_dpp v41, -v50, v1 row_newbcast:1 row_mask:0xf bank_mask:0xf
	v_fmac_f32_dpp v40, -v50, v2 row_newbcast:2 row_mask:0xf bank_mask:0xf
	v_fmac_f32_dpp v41, -v50, v3 row_newbcast:3 row_mask:0xf bank_mask:0xf
	v_fmac_f32_dpp v40, -v50, v4 row_newbcast:4 row_mask:0xf bank_mask:0xf
	ds_read_b32 v57, v38 offset:13312
	ds_read_b32 v50, v37 offset:3328
	v_add_f32_e32 v42, v40, v41
	v_mov_b32_e32 v43, v42
	s_nop 1
	v_permlane32_swap_b32_e32 v42, v43
	s_nop 1
	v_add_f32_dpp v5, v42, v43 quad_perm:[0,1,2,3] row_mask:0x3 bank_mask:0xf
	s_waitcnt lgkmcnt(6)
	v_mul_f32_e32 v40, v58, v39
	v_mov_b32_e32 v41, 0
	v_fmac_f32_dpp v40, -v52, v0 row_newbcast:0 row_mask:0xf bank_mask:0xf
	v_fmac_f32_dpp v41, -v52, v1 row_newbcast:1 row_mask:0xf bank_mask:0xf
	v_fmac_f32_dpp v40, -v52, v2 row_newbcast:2 row_mask:0xf bank_mask:0xf
	v_fmac_f32_dpp v41, -v52, v3 row_newbcast:3 row_mask:0xf bank_mask:0xf
	v_fmac_f32_dpp v40, -v52, v4 row_newbcast:4 row_mask:0xf bank_mask:0xf
	v_fmac_f32_dpp v41, -v52, v5 row_newbcast:5 row_mask:0xf bank_mask:0xf
	ds_read_b32 v58, v38 offset:14336
	ds_read_b32 v52, v37 offset:3584
	v_add_f32_e32 v42, v40, v41
	v_mov_b32_e32 v43, v42
	s_nop 1
	v_permlane32_swap_b32_e32 v42, v43
	s_nop 1
	v_add_f32_dpp v4, v42, v43 quad_perm:[0,1,2,3] row_mask:0xc bank_mask:0xf
	s_waitcnt lgkmcnt(6)
	v_mul_f32_e32 v40, v59, v39
	v_mov_b32_e32 v41, 0
	v_fmac_f32_dpp v40, -v54, v0 row_newbcast:0 row_mask:0xf bank_mask:0xf
	v_fmac_f32_dpp v41, -v54, v1 row_newbcast:1 row_mask:0xf bank_mask:0xf
	v_fmac_f32_dpp v40, -v54, v2 row_newbcast:2 row_mask:0xf bank_mask:0xf
	v_fmac_f32_dpp v41, -v54, v3 row_newbcast:3 row_mask:0xf bank_mask:0xf
	v_fmac_f32_dpp v40, -v54, v4 row_newbcast:4 row_mask:0xf bank_mask:0xf
	v_fmac_f32_dpp v41, -v54, v5 row_newbcast:5 row_mask:0xf bank_mask:0xf
	ds_read_b32 v59, v38 offset:15360
	ds_read_b32 v54, v37 offset:3840
	v_add_f32_e32 v42, v40, v41
	v_mov_b32_e32 v43, v42
	s_nop 1
	v_permlane32_swap_b32_e32 v42, v43
	s_nop 1
	v_add_f32_dpp v5, v42, v43 quad_perm:[0,1,2,3] row_mask:0xc bank_mask:0xf
	s_waitcnt lgkmcnt(6)
	v_mul_f32_e32 v40, v56, v39
	v_mov_b32_e32 v41, 0
	v_fmac_f32_dpp v40, -v48, v0 row_newbcast:0 row_mask:0xf bank_mask:0xf
	v_fmac_f32_dpp v41, -v48, v1 row_newbcast:1 row_mask:0xf bank_mask:0xf
	v_fmac_f32_dpp v40, -v48, v2 row_newbcast:2 row_mask:0xf bank_mask:0xf
	v_fmac_f32_dpp v41, -v48, v3 row_newbcast:3 row_mask:0xf bank_mask:0xf
	v_fmac_f32_dpp v40, -v48, v4 row_newbcast:4 row_mask:0xf bank_mask:0xf
	v_fmac_f32_dpp v41, -v48, v5 row_newbcast:5 row_mask:0xf bank_mask:0xf
	ds_read_b32 v56, v38 offset:16384
	ds_read_b32 v48, v37 offset:4096
	v_add_f32_e32 v42, v40, v41
	v_mov_b32_e32 v43, v42
	s_nop 1
	v_permlane32_swap_b32_e32 v42, v43
	s_nop 1
	v_add_f32_dpp v6, v42, v43 quad_perm:[0,1,2,3] row_mask:0x3 bank_mask:0xf
	s_waitcnt lgkmcnt(6)
	v_mul_f32_e32 v40, v57, v39
	v_mov_b32_e32 v41, 0
	v_fmac_f32_dpp v40, -v50, v0 row_newbcast:0 row_mask:0xf bank_mask:0xf
	v_fmac_f32_dpp v41, -v50, v1 row_newbcast:1 row_mask:0xf bank_mask:0xf
	v_fmac_f32_dpp v40, -v50, v2 row_newbcast:2 row_mask:0xf bank_mask:0xf
	v_fmac_f32_dpp v41, -v50, v3 row_newbcast:3 row_mask:0xf bank_mask:0xf
	v_fmac_f32_dpp v40, -v50, v4 row_newbcast:4 row_mask:0xf bank_mask:0xf
	v_fmac_f32_dpp v41, -v50, v5 row_newbcast:5 row_mask:0xf bank_mask:0xf
	v_fmac_f32_dpp v40, -v50, v6 row_newbcast:6 row_mask:0xf bank_mask:0xf
	ds_read_b32 v57, v38 offset:17408
	ds_read_b32 v50, v37 offset:4352
	v_add_f32_e32 v42, v40, v41
	v_mov_b32_e32 v43, v42
	s_nop 1
	v_permlane32_swap_b32_e32 v42, v43
	s_nop 1
	v_add_f32_dpp v7, v42, v43 quad_perm:[0,1,2,3] row_mask:0x3 bank_mask:0xf
	s_waitcnt lgkmcnt(6)
	v_mul_f32_e32 v40, v58, v39
	v_mov_b32_e32 v41, 0
	v_fmac_f32_dpp v40, -v52, v0 row_newbcast:0 row_mask:0xf bank_mask:0xf
	v_fmac_f32_dpp v41, -v52, v1 row_newbcast:1 row_mask:0xf bank_mask:0xf
	v_fmac_f32_dpp v40, -v52, v2 row_newbcast:2 row_mask:0xf bank_mask:0xf
	v_fmac_f32_dpp v41, -v52, v3 row_newbcast:3 row_mask:0xf bank_mask:0xf
	v_fmac_f32_dpp v40, -v52, v4 row_newbcast:4 row_mask:0xf bank_mask:0xf
	v_fmac_f32_dpp v41, -v52, v5 row_newbcast:5 row_mask:0xf bank_mask:0xf
	v_fmac_f32_dpp v40, -v52, v6 row_newbcast:6 row_mask:0xf bank_mask:0xf
	v_fmac_f32_dpp v41, -v52, v7 row_newbcast:7 row_mask:0xf bank_mask:0xf
	ds_read_b32 v58, v38 offset:18432
	ds_read_b32 v52, v37 offset:4608
	v_add_f32_e32 v42, v40, v41
	v_mov_b32_e32 v43, v42
	s_nop 1
	v_permlane32_swap_b32_e32 v42, v43
	s_nop 1
	v_add_f32_dpp v6, v42, v43 quad_perm:[0,1,2,3] row_mask:0xc bank_mask:0xf
	s_waitcnt lgkmcnt(6)
; #define LAS __attribute__((address_space(3)))
; __device__ __forceinline__ void phase_chunk_prep(const Params& p, LAS unsigned char* lds, int wave_s) {
;     ...
;             for (int i = 0; i < 64; ++i) {
;                 float s0 = RHS[i * 256 + col], s1 = 0.f, s2 = 0.f, s3 = 0.f;
; #pragma unroll
;                 for (int j4 = 0; j4 < (i + 3) / 4; ++j4) { const f32x4 a = *(const LAS f32x4*)(AM + i * 64 + 4 * j4);
;                     s0 -= a.x * sol[4 * j4]; s1 -= a.y * sol[4 * j4 + 1]; s2 -= a.z * sol[4 * j4 + 2]; s3 -= a.w * sol[4 * j4 + 3]; }
;                 sol[i] = (s0 + s1) + (s2 + s3);
;             }
	v_mul_f32_e32 v40, v59, v39
	v_mov_b32_e32 v41, 0
	v_fmac_f32_dpp v40, -v54, v0 row_newbcast:0 row_mask:0xf bank_mask:0xf
	v_fmac_f32_dpp v41, -v54, v1 row_newbcast:1 row_mask:0xf bank_mask:0xf
	v_fmac_f32_dpp v40, -v54, v2 row_newbcast:2 row_mask:0xf bank_mask:0xf
	v_fmac_f32_dpp v41, -v54, v3 row_newbcast:3 row_mask:0xf bank_mask:0xf
	v_fmac_f32_dpp v40, -v54, v4 row_newbcast:4 row_mask:0xf bank_mask:0xf
	v_fmac_f32_dpp v41, -v54, v5 row_newbcast:5 row_mask:0xf bank_mask:0xf
	v_fmac_f32_dpp v40, -v54, v6 row_newbcast:6 row_mask:0xf bank_mask:0xf
	v_fmac_f32_dpp v41, -v54, v7 row_newbcast:7 row_mask:0xf bank_mask:0xf
	ds_read_b32 v59, v38 offset:19456
	ds_read_b32 v54, v37 offset:4864
	v_add_f32_e32 v42, v40, v41
	v_mov_b32_e32 v43, v42
	s_nop 1
	v_permlane32_swap_b32_e32 v42, v43
	s_nop 1
	v_add_f32_dpp v7, v42, v43 quad_perm:[0,1,2,3] row_mask:0xc bank_mask:0xf
	s_waitcnt lgkmcnt(6)
	v_mul_f32_e32 v40, v56, v39
	v_mov_b32_e32 v41, 0
	v_fmac_f32_dpp v40, -v48, v0 row_newbcast:0 row_mask:0xf bank_mask:0xf
	v_fmac_f32_dpp v41, -v48, v1 row_newbcast:1 row_mask:0xf bank_mask:0xf
	v_fmac_f32_dpp v40, -v48, v2 row_newbcast:2 row_mask:0xf bank_mask:0xf
	v_fmac_f32_dpp v41, -v48, v3 row_newbcast:3 row_mask:0xf bank_mask:0xf
	v_fmac_f32_dpp v40, -v48, v4 row_newbcast:4 row_mask:0xf bank_mask:0xf
	v_fmac_f32_dpp v41, -v48, v5 row_newbcast:5 row_mask:0xf bank_mask:0xf
	v_fmac_f32_dpp v40, -v48, v6 row_newbcast:6 row_mask:0xf bank_mask:0xf
	v_fmac_f32_dpp v41, -v48, v7 row_newbcast:7 row_mask:0xf bank_mask:0xf
	ds_read_b32 v56, v38 offset:20480
	ds_read_b32 v48, v37 offset:5120
	v_add_f32_e32 v42, v40, v41
	v_mov_b32_e32 v43, v42
	s_nop 1
	v_permlane32_swap_b32_e32 v42, v43
	s_nop 1
	v_add_f32_dpp v8, v42, v43 quad_perm:[0,1,2,3] row_mask:0x3 bank_mask:0xf
	s_waitcnt lgkmcnt(6)
	v_mul_f32_e32 v40, v57, v39
	v_mov_b32_e32 v41, 0
	v_fmac_f32_dpp v40, -v50, v0 row_newbcast:0 row_mask:0xf bank_mask:0xf
	v_fmac_f32_dpp v41, -v50, v1 row_newbcast:1 row_mask:0xf bank_mask:0xf
	v_fmac_f32_dpp v40, -v50, v2 row_newbcast:2 row_mask:0xf bank_mask:0xf
	v_fmac_f32_dpp v41, -v50, v3 row_newbcast:3 row_mask:0xf bank_mask:0xf
	v_fmac_f32_dpp v40, -v50, v4 row_newbcast:4 row_mask:0xf bank_mask:0xf
	v_fmac_f32_dpp v41, -v50, v5 row_newbcast:5 row_mask:0xf bank_mask:0xf
	v_fmac_f32_dpp v40, -v50, v6 row_newbcast:6 row_mask:0xf bank_mask:0xf
	v_fmac_f32_dpp v41, -v50, v7 row_newbcast:7 row_mask:0xf bank_mask:0xf
	v_fmac_f32_dpp v40, -v50, v8 row_newbcast:8 row_mask:0xf bank_mask:0xf
	ds_read_b32 v57, v38 offset:21504
	ds_read_b32 v50, v37 offset:5376
	v_add_f32_e32 v42, v40, v41
	v_mov_b32_e32 v43, v42
	s_nop 1
	v_permlane32_swap_b32_e32 v42, v43
	s_nop 1
	v_add_f32_dpp v9, v42, v43 quad_perm:[0,1,2,3] row_mask:0x3 bank_mask:0xf
	s_waitcnt lgkmcnt(6)
	v_mul_f32_e32 v40, v58, v39
	v_mov_b32_e32 v41, 0
	v_fmac_f32_dpp v40, -v52, v0 row_newbcast:0 row_mask:0xf bank_mask:0xf
	v_fmac_f32_dpp v41, -v52, v1 row_newbcast:1 row_mask:0xf bank_mask:0xf
	v_fmac_f32_dpp v40, -v52, v2 row_newbcast:2 row_mask:0xf bank_mask:0xf
	v_fmac_f32_dpp v41, -v52, v3 row_newbcast:3 row_mask:0xf bank_mask:0xf
	v_fmac_f32_dpp v40, -v52, v4 row_newbcast:4 row_mask:0xf bank_mask:0xf
	v_fmac_f32_dpp v41, -v52, v5 row_newbcast:5 row_mask:0xf bank_mask:0xf
	v_fmac_f32_dpp v40, -v52, v6 row_newbcast:6 row_mask:0xf bank_mask:0xf
	v_fmac_f32_dpp v41, -v52, v7 row_newbcast:7 row_mask:0xf bank_mask:0xf
	v_fmac_f32_dpp v40, -v52, v8 row_newbcast:8 row_mask:0xf bank_mask:0xf
	v_fmac_f32_dpp v41, -v52, v9 row_newbcast:9 row_mask:0xf bank_mask:0xf
	ds_read_b32 v58, v38 offset:22528
	ds_read_b32 v52, v37 offset:5632
	v_add_f32_e32 v42, v40, v41
	v_mov_b32_e32 v43, v42
	s_nop 1
	v_permlane32_swap_b32_e32 v42, v43
	s_nop 1
	v_add_f32_dpp v8, v42, v43 quad_perm:[0,1,2,3] row_mask:0xc bank_mask:0xf
	s_waitcnt lgkmcnt(6)
	v_mul_f32_e32 v40, v59, v39
	v_mov_b32_e32 v41, 0
	v_fmac_f32_dpp v40, -v54, v0 row_newbcast:0 row_mask:0xf bank_mask:0xf
	v_fmac_f32_dpp v41, -v54, v1 row_newbcast:1 row_mask:0xf bank_mask:0xf
	v_fmac_f32_dpp v40, -v54, v2 row_newbcast:2 row_mask:0xf bank_mask:0xf
	v_fmac_f32_dpp v41, -v54, v3 row_newbcast:3 row_mask:0xf bank_mask:0xf
	v_fmac_f32_dpp v40, -v54, v4 row_newbcast:4 row_mask:0xf bank_mask:0xf
	v_fmac_f32_dpp v41, -v54, v5 row_newbcast:5 row_mask:0xf bank_mask:0xf
	v_fmac_f32_dpp v40, -v54, v6 row_newbcast:6 row_mask:0xf bank_mask:0xf
	v_fmac_f32_dpp v41, -v54, v7 row_newbcast:7 row_mask:0xf bank_mask:0xf
	v_fmac_f32_dpp v40, -v54, v8 row_newbcast:8 row_mask:0xf bank_mask:0xf
	v_fmac_f32_dpp v41, -v54, v9 row_newbcast:9 row_mask:0xf bank_mask:0xf
	ds_read_b32 v59, v38 offset:23552
	ds_read_b32 v54, v37 offset:5888
	v_add_f32_e32 v42, v40, v41
	v_mov_b32_e32 v43, v42
	s_nop 1
	v_permlane32_swap_b32_e32 v42, v43
	s_nop 1
	v_add_f32_dpp v9, v42, v43 quad_perm:[0,1,2,3] row_mask:0xc bank_mask:0xf
	s_waitcnt lgkmcnt(6)
	v_mul_f32_e32 v40, v56, v39
	v_mov_b32_e32 v41, 0
	v_fmac_f32_dpp v40, -v48, v0 row_newbcast:0 row_mask:0xf bank_mask:0xf
	v_fmac_f32_dpp v41, -v48, v1 row_newbcast:1 row_mask:0xf bank_mask:0xf
	v_fmac_f32_dpp v40, -v48, v2 row_newbcast:2 row_mask:0xf bank_mask:0xf
	v_fmac_f32_dpp v41, -v48, v3 row_newbcast:3 row_mask:0xf bank_mask:0xf
	v_fmac_f32_dpp v40, -v48, v4 row_newbcast:4 row_mask:0xf bank_mask:0xf
	v_fmac_f32_dpp v41, -v48, v5 row_newbcast:5 row_mask:0xf bank_mask:0xf
	v_fmac_f32_dpp v40, -v48, v6 row_newbcast:6 row_mask:0xf bank_mask:0xf
	v_fmac_f32_dpp v41, -v48, v7 row_newbcast:7 row_mask:0xf bank_mask:0xf
	v_fmac_f32_dpp v40, -v48, v8 row_newbcast:8 row_mask:0xf bank_mask:0xf
	v_fmac_f32_dpp v41, -v48, v9 row_newbcast:9 row_mask:0xf bank_mask:0xf
	ds_read_b32 v56, v38 offset:24576
	ds_read_b32 v48, v37 offset:6144
	v_add_f32_e32 v42, v40, v41
	v_mov_b32_e32 v43, v42
	s_nop 1
	v_permlane32_swap_b32_e32 v42, v43
	s_nop 1
	v_add_f32_dpp v10, v42, v43 quad_perm:[0,1,2,3] row_mask:0x3 bank_mask:0xf
	s_waitcnt lgkmcnt(6)
; #define LAS __attribute__((address_space(3)))
; __device__ __forceinline__ void phase_chunk_prep(const Params& p, LAS unsigned char* lds, int wave_s) {
;     ...
;             for (int i = 0; i < 64; ++i) {
;                 float s0 = RHS[i * 256 + col], s1 = 0.f, s2 = 0.f, s3 = 0.f;
; #pragma unroll
;                 for (int j4 = 0; j4 < (i + 3) / 4; ++j4) { const f32x4 a = *(const LAS f32x4*)(AM + i * 64 + 4 * j4);
;                     s0 -= a.x * sol[4 * j4]; s1 -= a.y * sol[4 * j4 + 1]; s2 -= a.z * sol[4 * j4 + 2]; s3 -= a.w * sol[4 * j4 + 3]; }
;                 sol[i] = (s0 + s1) + (s2 + s3);
;             }
	v_mul_f32_e32 v40, v57, v39
	v_mov_b32_e32 v41, 0
	v_fmac_f32_dpp v40, -v50, v0 row_newbcast:0 row_mask:0xf bank_mask:0xf
	v_fmac_f32_dpp v41, -v50, v1 row_newbcast:1 row_mask:0xf bank_mask:0xf
	v_fmac_f32_dpp v40, -v50, v2 row_newbcast:2 row_mask:0xf bank_mask:0xf
	v_fmac_f32_dpp v41, -v50, v3 row_newbcast:3 row_mask:0xf bank_mask:0xf
	v_fmac_f32_dpp v40, -v50, v4 row_newbcast:4 row_mask:0xf bank_mask:0xf
	v_fmac_f32_dpp v41, -v50, v5 row_newbcast:5 row_mask:0xf bank_mask:0xf
	v_fmac_f32_dpp v40, -v50, v6 row_newbcast:6 row_mask:0xf bank_mask:0xf
	v_fmac_f32_dpp v41, -v50, v7 row_newbcast:7 row_mask:0xf bank_mask:0xf
	v_fmac_f32_dpp v40, -v50, v8 row_newbcast:8 row_mask:0xf bank_mask:0xf
	v_fmac_f32_dpp v41, -v50, v9 row_newbcast:9 row_mask:0xf bank_mask:0xf
	v_fmac_f32_dpp v40, -v50, v10 row_newbcast:10 row_mask:0xf bank_mask:0xf
	ds_read_b32 v57, v38 offset:25600
	ds_read_b32 v50, v37 offset:6400
	v_add_f32_e32 v42, v40, v41
	v_mov_b32_e32 v43, v42
	s_nop 1
	v_permlane32_swap_b32_e32 v42, v43
	s_nop 1
	v_add_f32_dpp v11, v42, v43 quad_perm:[0,1,2,3] row_mask:0x3 bank_mask:0xf
	s_waitcnt lgkmcnt(6)
	v_mul_f32_e32 v40, v58, v39
	v_mov_b32_e32 v41, 0
	v_fmac_f32_dpp v40, -v52, v0 row_newbcast:0 row_mask:0xf bank_mask:0xf
	v_fmac_f32_dpp v41, -v52, v1 row_newbcast:1 row_mask:0xf bank_mask:0xf
	v_fmac_f32_dpp v40, -v52, v2 row_newbcast:2 row_mask:0xf bank_mask:0xf
	v_fmac_f32_dpp v41, -v52, v3 row_newbcast:3 row_mask:0xf bank_mask:0xf
	v_fmac_f32_dpp v40, -v52, v4 row_newbcast:4 row_mask:0xf bank_mask:0xf
	v_fmac_f32_dpp v41, -v52, v5 row_newbcast:5 row_mask:0xf bank_mask:0xf
	v_fmac_f32_dpp v40, -v52, v6 row_newbcast:6 row_mask:0xf bank_mask:0xf
	v_fmac_f32_dpp v41, -v52, v7 row_newbcast:7 row_mask:0xf bank_mask:0xf
	v_fmac_f32_dpp v40, -v52, v8 row_newbcast:8 row_mask:0xf bank_mask:0xf
	v_fmac_f32_dpp v41, -v52, v9 row_newbcast:9 row_mask:0xf bank_mask:0xf
	v_fmac_f32_dpp v40, -v52, v10 row_newbcast:10 row_mask:0xf bank_mask:0xf
	v_fmac_f32_dpp v41, -v52, v11 row_newbcast:11 row_mask:0xf bank_mask:0xf
	ds_read_b32 v58, v38 offset:26624
	ds_read_b32 v52, v37 offset:6656
	v_add_f32_e32 v42, v40, v41
	v_mov_b32_e32 v43, v42
	s_nop 1
	v_permlane32_swap_b32_e32 v42, v43
	s_nop 1
	v_add_f32_dpp v10, v42, v43 quad_perm:[0,1,2,3] row_mask:0xc bank_mask:0xf
	s_waitcnt lgkmcnt(6)
	v_mul_f32_e32 v40, v59, v39
	v_mov_b32_e32 v41, 0
	v_fmac_f32_dpp v40, -v54, v0 row_newbcast:0 row_mask:0xf bank_mask:0xf
	v_fmac_f32_dpp v41, -v54, v1 row_newbcast:1 row_mask:0xf bank_mask:0xf
	v_fmac_f32_dpp v40, -v54, v2 row_newbcast:2 row_mask:0xf bank_mask:0xf
	v_fmac_f32_dpp v41, -v54, v3 row_newbcast:3 row_mask:0xf bank_mask:0xf
	v_fmac_f32_dpp v40, -v54, v4 row_newbcast:4 row_mask:0xf bank_mask:0xf
	v_fmac_f32_dpp v41, -v54, v5 row_newbcast:5 row_mask:0xf bank_mask:0xf
	v_fmac_f32_dpp v40, -v54, v6 row_newbcast:6 row_mask:0xf bank_mask:0xf
	v_fmac_f32_dpp v41, -v54, v7 row_newbcast:7 row_mask:0xf bank_mask:0xf
	v_fmac_f32_dpp v40, -v54, v8 row_newbcast:8 row_mask:0xf bank_mask:0xf
	v_fmac_f32_dpp v41, -v54, v9 row_newbcast:9 row_mask:0xf bank_mask:0xf
	v_fmac_f32_dpp v40, -v54, v10 row_newbcast:10 row_mask:0xf bank_mask:0xf
	v_fmac_f32_dpp v41, -v54, v11 row_newbcast:11 row_mask:0xf bank_mask:0xf
	ds_read_b32 v59, v38 offset:27648
	ds_read_b32 v54, v37 offset:6912
	v_add_f32_e32 v42, v40, v41
	v_mov_b32_e32 v43, v42
	s_nop 1
	v_permlane32_swap_b32_e32 v42, v43
	s_nop 1
	v_add_f32_dpp v11, v42, v43 quad_perm:[0,1,2,3] row_mask:0xc bank_mask:0xf
	s_waitcnt lgkmcnt(6)
	v_mul_f32_e32 v40, v56, v39
	v_mov_b32_e32 v41, 0
	v_fmac_f32_dpp v40, -v48, v0 row_newbcast:0 row_mask:0xf bank_mask:0xf
	v_fmac_f32_dpp v41, -v48, v1 row_newbcast:1 row_mask:0xf bank_mask:0xf
	v_fmac_f32_dpp v40, -v48, v2 row_newbcast:2 row_mask:0xf bank_mask:0xf
	v_fmac_f32_dpp v41, -v48, v3 row_newbcast:3 row_mask:0xf bank_mask:0xf
	v_fmac_f32_dpp v40, -v48, v4 row_newbcast:4 row_mask:0xf bank_mask:0xf
	v_fmac_f32_dpp v41, -v48, v5 row_newbcast:5 row_mask:0xf bank_mask:0xf
	v_fmac_f32_dpp v40, -v48, v6 row_newbcast:6 row_mask:0xf bank_mask:0xf
	v_fmac_f32_dpp v41, -v48, v7 row_newbcast:7 row_mask:0xf bank_mask:0xf
	v_fmac_f32_dpp v40, -v48, v8 row_newbcast:8 row_mask:0xf bank_mask:0xf
	v_fmac_f32_dpp v41, -v48, v9 row_newbcast:9 row_mask:0xf bank_mask:0xf
	v_fmac_f32_dpp v40, -v48, v10 row_newbcast:10 row_mask:0xf bank_mask:0xf
	v_fmac_f32_dpp v41, -v48, v11 row_newbcast:11 row_mask:0xf bank_mask:0xf
	ds_read_b32 v56, v38 offset:28672
	ds_read_b32 v48, v37 offset:7168
	v_add_f32_e32 v42, v40, v41
	v_mov_b32_e32 v43, v42
	s_nop 1
	v_permlane32_swap_b32_e32 v42, v43
	s_nop 1
	v_add_f32_dpp v12, v42, v43 quad_perm:[0,1,2,3] row_mask:0x3 bank_mask:0xf
	s_waitcnt lgkmcnt(6)
	v_mul_f32_e32 v40, v57, v39
	v_mov_b32_e32 v41, 0
	v_fmac_f32_dpp v40, -v50, v0 row_newbcast:0 row_mask:0xf bank_mask:0xf
	v_fmac_f32_dpp v41, -v50, v1 row_newbcast:1 row_mask:0xf bank_mask:0xf
	v_fmac_f32_dpp v40, -v50, v2 row_newbcast:2 row_mask:0xf bank_mask:0xf
	v_fmac_f32_dpp v41, -v50, v3 row_newbcast:3 row_mask:0xf bank_mask:0xf
	v_fmac_f32_dpp v40, -v50, v4 row_newbcast:4 row_mask:0xf bank_mask:0xf
	v_fmac_f32_dpp v41, -v50, v5 row_newbcast:5 row_mask:0xf bank_mask:0xf
	v_fmac_f32_dpp v40, -v50, v6 row_newbcast:6 row_mask:0xf bank_mask:0xf
	v_fmac_f32_dpp v41, -v50, v7 row_newbcast:7 row_mask:0xf bank_mask:0xf
	v_fmac_f32_dpp v40, -v50, v8 row_newbcast:8 row_mask:0xf bank_mask:0xf
	v_fmac_f32_dpp v41, -v50, v9 row_newbcast:9 row_mask:0xf bank_mask:0xf
	v_fmac_f32_dpp v40, -v50, v10 row_newbcast:10 row_mask:0xf bank_mask:0xf
	v_fmac_f32_dpp v41, -v50, v11 row_newbcast:11 row_mask:0xf bank_mask:0xf
	v_fmac_f32_dpp v40, -v50, v12 row_newbcast:12 row_mask:0xf bank_mask:0xf
	ds_read_b32 v57, v38 offset:29696
	ds_read_b32 v50, v37 offset:7424
	v_add_f32_e32 v42, v40, v41
	v_mov_b32_e32 v43, v42
	s_nop 1
	v_permlane32_swap_b32_e32 v42, v43
	s_nop 1
	v_add_f32_dpp v13, v42, v43 quad_perm:[0,1,2,3] row_mask:0x3 bank_mask:0xf
	s_waitcnt lgkmcnt(6)
; #define LAS __attribute__((address_space(3)))
; __device__ __forceinline__ void phase_chunk_prep(const Params& p, LAS unsigned char* lds, int wave_s) {
;     ...
;             for (int i = 0; i < 64; ++i) {
;                 float s0 = RHS[i * 256 + col], s1 = 0.f, s2 = 0.f, s3 = 0.f;
; #pragma unroll
;                 for (int j4 = 0; j4 < (i + 3) / 4; ++j4) { const f32x4 a = *(const LAS f32x4*)(AM + i * 64 + 4 * j4);
;                     s0 -= a.x * sol[4 * j4]; s1 -= a.y * sol[4 * j4 + 1]; s2 -= a.z * sol[4 * j4 + 2]; s3 -= a.w * sol[4 * j4 + 3]; }
;                 sol[i] = (s0 + s1) + (s2 + s3);
;             }
	v_mul_f32_e32 v40, v58, v39
	v_mov_b32_e32 v41, 0
	v_fmac_f32_dpp v40, -v52, v0 row_newbcast:0 row_mask:0xf bank_mask:0xf
	v_fmac_f32_dpp v41, -v52, v1 row_newbcast:1 row_mask:0xf bank_mask:0xf
	v_fmac_f32_dpp v40, -v52, v2 row_newbcast:2 row_mask:0xf bank_mask:0xf
	v_fmac_f32_dpp v41, -v52, v3 row_newbcast:3 row_mask:0xf bank_mask:0xf
	v_fmac_f32_dpp v40, -v52, v4 row_newbcast:4 row_mask:0xf bank_mask:0xf
	v_fmac_f32_dpp v41, -v52, v5 row_newbcast:5 row_mask:0xf bank_mask:0xf
	v_fmac_f32_dpp v40, -v52, v6 row_newbcast:6 row_mask:0xf bank_mask:0xf
	v_fmac_f32_dpp v41, -v52, v7 row_newbcast:7 row_mask:0xf bank_mask:0xf
	v_fmac_f32_dpp v40, -v52, v8 row_newbcast:8 row_mask:0xf bank_mask:0xf
	v_fmac_f32_dpp v41, -v52, v9 row_newbcast:9 row_mask:0xf bank_mask:0xf
	v_fmac_f32_dpp v40, -v52, v10 row_newbcast:10 row_mask:0xf bank_mask:0xf
	v_fmac_f32_dpp v41, -v52, v11 row_newbcast:11 row_mask:0xf bank_mask:0xf
	v_fmac_f32_dpp v40, -v52, v12 row_newbcast:12 row_mask:0xf bank_mask:0xf
	v_fmac_f32_dpp v41, -v52, v13 row_newbcast:13 row_mask:0xf bank_mask:0xf
	ds_read_b32 v58, v38 offset:30720
	ds_read_b32 v52, v37 offset:7680
	v_add_f32_e32 v42, v40, v41
	v_mov_b32_e32 v43, v42
	s_nop 1
	v_permlane32_swap_b32_e32 v42, v43
	s_nop 1
	v_add_f32_dpp v12, v42, v43 quad_perm:[0,1,2,3] row_mask:0xc bank_mask:0xf
	s_waitcnt lgkmcnt(6)
	v_mul_f32_e32 v40, v59, v39
	v_mov_b32_e32 v41, 0
	v_fmac_f32_dpp v40, -v54, v0 row_newbcast:0 row_mask:0xf bank_mask:0xf
	v_fmac_f32_dpp v41, -v54, v1 row_newbcast:1 row_mask:0xf bank_mask:0xf
	v_fmac_f32_dpp v40, -v54, v2 row_newbcast:2 row_mask:0xf bank_mask:0xf
	v_fmac_f32_dpp v41, -v54, v3 row_newbcast:3 row_mask:0xf bank_mask:0xf
	v_fmac_f32_dpp v40, -v54, v4 row_newbcast:4 row_mask:0xf bank_mask:0xf
	v_fmac_f32_dpp v41, -v54, v5 row_newbcast:5 row_mask:0xf bank_mask:0xf
	v_fmac_f32_dpp v40, -v54, v6 row_newbcast:6 row_mask:0xf bank_mask:0xf
	v_fmac_f32_dpp v41, -v54, v7 row_newbcast:7 row_mask:0xf bank_mask:0xf
	v_fmac_f32_dpp v40, -v54, v8 row_newbcast:8 row_mask:0xf bank_mask:0xf
	v_fmac_f32_dpp v41, -v54, v9 row_newbcast:9 row_mask:0xf bank_mask:0xf
	v_fmac_f32_dpp v40, -v54, v10 row_newbcast:10 row_mask:0xf bank_mask:0xf
	v_fmac_f32_dpp v41, -v54, v11 row_newbcast:11 row_mask:0xf bank_mask:0xf
	v_fmac_f32_dpp v40, -v54, v12 row_newbcast:12 row_mask:0xf bank_mask:0xf
	v_fmac_f32_dpp v41, -v54, v13 row_newbcast:13 row_mask:0xf bank_mask:0xf
	ds_read_b32 v59, v38 offset:31744
	ds_read_b32 v54, v37 offset:7936
	v_add_f32_e32 v42, v40, v41
	v_mov_b32_e32 v43, v42
	s_nop 1
	v_permlane32_swap_b32_e32 v42, v43
	s_nop 1
	v_add_f32_dpp v13, v42, v43 quad_perm:[0,1,2,3] row_mask:0xc bank_mask:0xf
	s_waitcnt lgkmcnt(6)
	v_mul_f32_e32 v40, v56, v39
	v_mov_b32_e32 v41, 0
	v_fmac_f32_dpp v40, -v48, v0 row_newbcast:0 row_mask:0xf bank_mask:0xf
	v_fmac_f32_dpp v41, -v48, v1 row_newbcast:1 row_mask:0xf bank_mask:0xf
	v_fmac_f32_dpp v40, -v48, v2 row_newbcast:2 row_mask:0xf bank_mask:0xf
	v_fmac_f32_dpp v41, -v48, v3 row_newbcast:3 row_mask:0xf bank_mask:0xf
	v_fmac_f32_dpp v40, -v48, v4 row_newbcast:4 row_mask:0xf bank_mask:0xf
	v_fmac_f32_dpp v41, -v48, v5 row_newbcast:5 row_mask:0xf bank_mask:0xf
	v_fmac_f32_dpp v40, -v48, v6 row_newbcast:6 row_mask:0xf bank_mask:0xf
	v_fmac_f32_dpp v41, -v48, v7 row_newbcast:7 row_mask:0xf bank_mask:0xf
	v_fmac_f32_dpp v40, -v48, v8 row_newbcast:8 row_mask:0xf bank_mask:0xf
	v_fmac_f32_dpp v41, -v48, v9 row_newbcast:9 row_mask:0xf bank_mask:0xf
	v_fmac_f32_dpp v40, -v48, v10 row_newbcast:10 row_mask:0xf bank_mask:0xf
	v_fmac_f32_dpp v41, -v48, v11 row_newbcast:11 row_mask:0xf bank_mask:0xf
	v_fmac_f32_dpp v40, -v48, v12 row_newbcast:12 row_mask:0xf bank_mask:0xf
	v_fmac_f32_dpp v41, -v48, v13 row_newbcast:13 row_mask:0xf bank_mask:0xf
	ds_read_b32 v56, v38 offset:32768
	ds_read_b32 v48, v37 offset:8192
	v_add_f32_e32 v42, v40, v41
	v_mov_b32_e32 v43, v42
	s_nop 1
	v_permlane32_swap_b32_e32 v42, v43
	s_nop 1
	v_add_f32_dpp v14, v42, v43 quad_perm:[0,1,2,3] row_mask:0x3 bank_mask:0xf
	s_waitcnt lgkmcnt(6)
	v_mul_f32_e32 v40, v57, v39
	v_mov_b32_e32 v41, 0
	v_fmac_f32_dpp v40, -v50, v0 row_newbcast:0 row_mask:0xf bank_mask:0xf
	v_fmac_f32_dpp v41, -v50, v1 row_newbcast:1 row_mask:0xf bank_mask:0xf
	v_fmac_f32_dpp v40, -v50, v2 row_newbcast:2 row_mask:0xf bank_mask:0xf
	v_fmac_f32_dpp v41, -v50, v3 row_newbcast:3 row_mask:0xf bank_mask:0xf
	v_fmac_f32_dpp v40, -v50, v4 row_newbcast:4 row_mask:0xf bank_mask:0xf
	v_fmac_f32_dpp v41, -v50, v5 row_newbcast:5 row_mask:0xf bank_mask:0xf
	v_fmac_f32_dpp v40, -v50, v6 row_newbcast:6 row_mask:0xf bank_mask:0xf
	v_fmac_f32_dpp v41, -v50, v7 row_newbcast:7 row_mask:0xf bank_mask:0xf
	v_fmac_f32_dpp v40, -v50, v8 row_newbcast:8 row_mask:0xf bank_mask:0xf
	v_fmac_f32_dpp v41, -v50, v9 row_newbcast:9 row_mask:0xf bank_mask:0xf
	v_fmac_f32_dpp v40, -v50, v10 row_newbcast:10 row_mask:0xf bank_mask:0xf
	v_fmac_f32_dpp v41, -v50, v11 row_newbcast:11 row_mask:0xf bank_mask:0xf
	v_fmac_f32_dpp v40, -v50, v12 row_newbcast:12 row_mask:0xf bank_mask:0xf
	v_fmac_f32_dpp v41, -v50, v13 row_newbcast:13 row_mask:0xf bank_mask:0xf
	v_fmac_f32_dpp v40, -v50, v14 row_newbcast:14 row_mask:0xf bank_mask:0xf
	ds_read_b32 v57, v38 offset:33792
	ds_read_b32 v50, v37 offset:8448
	ds_read_b32 v51, v37 offset:8576
	v_add_f32_e32 v42, v40, v41
	v_mov_b32_e32 v43, v42
	s_nop 1
	v_permlane32_swap_b32_e32 v42, v43
	s_nop 1
	v_add_f32_dpp v15, v42, v43 quad_perm:[0,1,2,3] row_mask:0x3 bank_mask:0xf
	s_waitcnt lgkmcnt(7)
; #define LAS __attribute__((address_space(3)))
; __device__ __forceinline__ void phase_chunk_prep(const Params& p, LAS unsigned char* lds, int wave_s) {
;     ...
;             for (int i = 0; i < 64; ++i) {
;                 float s0 = RHS[i * 256 + col], s1 = 0.f, s2 = 0.f, s3 = 0.f;
; #pragma unroll
;                 for (int j4 = 0; j4 < (i + 3) / 4; ++j4) { const f32x4 a = *(const LAS f32x4*)(AM + i * 64 + 4 * j4);
;                     s0 -= a.x * sol[4 * j4]; s1 -= a.y * sol[4 * j4 + 1]; s2 -= a.z * sol[4 * j4 + 2]; s3 -= a.w * sol[4 * j4 + 3]; }
;                 sol[i] = (s0 + s1) + (s2 + s3);
;             }
	v_mul_f32_e32 v40, v58, v39
	v_mov_b32_e32 v41, 0
	v_fmac_f32_dpp v40, -v52, v0 row_newbcast:0 row_mask:0xf bank_mask:0xf
	v_fmac_f32_dpp v41, -v52, v1 row_newbcast:1 row_mask:0xf bank_mask:0xf
	v_fmac_f32_dpp v40, -v52, v2 row_newbcast:2 row_mask:0xf bank_mask:0xf
	v_fmac_f32_dpp v41, -v52, v3 row_newbcast:3 row_mask:0xf bank_mask:0xf
	v_fmac_f32_dpp v40, -v52, v4 row_newbcast:4 row_mask:0xf bank_mask:0xf
	v_fmac_f32_dpp v41, -v52, v5 row_newbcast:5 row_mask:0xf bank_mask:0xf
	v_fmac_f32_dpp v40, -v52, v6 row_newbcast:6 row_mask:0xf bank_mask:0xf
	v_fmac_f32_dpp v41, -v52, v7 row_newbcast:7 row_mask:0xf bank_mask:0xf
	v_fmac_f32_dpp v40, -v52, v8 row_newbcast:8 row_mask:0xf bank_mask:0xf
	v_fmac_f32_dpp v41, -v52, v9 row_newbcast:9 row_mask:0xf bank_mask:0xf
	v_fmac_f32_dpp v40, -v52, v10 row_newbcast:10 row_mask:0xf bank_mask:0xf
	v_fmac_f32_dpp v41, -v52, v11 row_newbcast:11 row_mask:0xf bank_mask:0xf
	v_fmac_f32_dpp v40, -v52, v12 row_newbcast:12 row_mask:0xf bank_mask:0xf
	v_fmac_f32_dpp v41, -v52, v13 row_newbcast:13 row_mask:0xf bank_mask:0xf
	v_fmac_f32_dpp v40, -v52, v14 row_newbcast:14 row_mask:0xf bank_mask:0xf
	v_fmac_f32_dpp v41, -v52, v15 row_newbcast:15 row_mask:0xf bank_mask:0xf
	ds_read_b32 v58, v38 offset:34816
	ds_read_b32 v52, v37 offset:8704
	ds_read_b32 v53, v37 offset:8832
	v_add_f32_e32 v42, v40, v41
	v_mov_b32_e32 v43, v42
	s_nop 1
	v_permlane32_swap_b32_e32 v42, v43
	s_nop 1
	v_add_f32_dpp v14, v42, v43 quad_perm:[0,1,2,3] row_mask:0xc bank_mask:0xf
	s_waitcnt lgkmcnt(8)
	v_mul_f32_e32 v40, v59, v39
	v_mov_b32_e32 v41, 0
	v_fmac_f32_dpp v40, -v54, v0 row_newbcast:0 row_mask:0xf bank_mask:0xf
	v_fmac_f32_dpp v41, -v54, v1 row_newbcast:1 row_mask:0xf bank_mask:0xf
	v_fmac_f32_dpp v40, -v54, v2 row_newbcast:2 row_mask:0xf bank_mask:0xf
	v_fmac_f32_dpp v41, -v54, v3 row_newbcast:3 row_mask:0xf bank_mask:0xf
	v_fmac_f32_dpp v40, -v54, v4 row_newbcast:4 row_mask:0xf bank_mask:0xf
	v_fmac_f32_dpp v41, -v54, v5 row_newbcast:5 row_mask:0xf bank_mask:0xf
	v_fmac_f32_dpp v40, -v54, v6 row_newbcast:6 row_mask:0xf bank_mask:0xf
	v_fmac_f32_dpp v41, -v54, v7 row_newbcast:7 row_mask:0xf bank_mask:0xf
	v_fmac_f32_dpp v40, -v54, v8 row_newbcast:8 row_mask:0xf bank_mask:0xf
	v_fmac_f32_dpp v41, -v54, v9 row_newbcast:9 row_mask:0xf bank_mask:0xf
	v_fmac_f32_dpp v40, -v54, v10 row_newbcast:10 row_mask:0xf bank_mask:0xf
	v_fmac_f32_dpp v41, -v54, v11 row_newbcast:11 row_mask:0xf bank_mask:0xf
	v_fmac_f32_dpp v40, -v54, v12 row_newbcast:12 row_mask:0xf bank_mask:0xf
	v_fmac_f32_dpp v41, -v54, v13 row_newbcast:13 row_mask:0xf bank_mask:0xf
	v_fmac_f32_dpp v40, -v54, v14 row_newbcast:14 row_mask:0xf bank_mask:0xf
	v_fmac_f32_dpp v41, -v54, v15 row_newbcast:15 row_mask:0xf bank_mask:0xf
	ds_read_b32 v59, v38 offset:35840
	ds_read_b32 v54, v37 offset:8960
	ds_read_b32 v55, v37 offset:9088
	v_add_f32_e32 v42, v40, v41
	v_mov_b32_e32 v43, v42
	s_nop 1
	v_permlane32_swap_b32_e32 v42, v43
	s_nop 1
	v_add_f32_dpp v15, v42, v43 quad_perm:[0,1,2,3] row_mask:0xc bank_mask:0xf
	s_waitcnt lgkmcnt(9)
	v_mul_f32_e32 v40, v56, v39
	v_mov_b32_e32 v41, 0
	v_fmac_f32_dpp v40, -v48, v0 row_newbcast:0 row_mask:0xf bank_mask:0xf
	v_fmac_f32_dpp v41, -v48, v1 row_newbcast:1 row_mask:0xf bank_mask:0xf
	v_fmac_f32_dpp v40, -v48, v2 row_newbcast:2 row_mask:0xf bank_mask:0xf
	v_fmac_f32_dpp v41, -v48, v3 row_newbcast:3 row_mask:0xf bank_mask:0xf
	v_fmac_f32_dpp v40, -v48, v4 row_newbcast:4 row_mask:0xf bank_mask:0xf
	v_fmac_f32_dpp v41, -v48, v5 row_newbcast:5 row_mask:0xf bank_mask:0xf
	v_fmac_f32_dpp v40, -v48, v6 row_newbcast:6 row_mask:0xf bank_mask:0xf
	v_fmac_f32_dpp v41, -v48, v7 row_newbcast:7 row_mask:0xf bank_mask:0xf
	v_fmac_f32_dpp v40, -v48, v8 row_newbcast:8 row_mask:0xf bank_mask:0xf
	v_fmac_f32_dpp v41, -v48, v9 row_newbcast:9 row_mask:0xf bank_mask:0xf
	v_fmac_f32_dpp v40, -v48, v10 row_newbcast:10 row_mask:0xf bank_mask:0xf
	v_fmac_f32_dpp v41, -v48, v11 row_newbcast:11 row_mask:0xf bank_mask:0xf
	v_fmac_f32_dpp v40, -v48, v12 row_newbcast:12 row_mask:0xf bank_mask:0xf
	v_fmac_f32_dpp v41, -v48, v13 row_newbcast:13 row_mask:0xf bank_mask:0xf
	v_fmac_f32_dpp v40, -v48, v14 row_newbcast:14 row_mask:0xf bank_mask:0xf
	v_fmac_f32_dpp v41, -v48, v15 row_newbcast:15 row_mask:0xf bank_mask:0xf
	ds_read_b32 v56, v38 offset:36864
	ds_read_b32 v48, v37 offset:9216
	ds_read_b32 v49, v37 offset:9344
	v_add_f32_e32 v42, v40, v41
	v_mov_b32_e32 v43, v42
	s_nop 1
	v_permlane32_swap_b32_e32 v42, v43
	s_nop 1
	v_add_f32_dpp v16, v42, v43 quad_perm:[0,1,2,3] row_mask:0x3 bank_mask:0xf
	s_waitcnt lgkmcnt(9)
	v_mul_f32_e32 v40, v57, v39
	v_mov_b32_e32 v41, 0
	v_fmac_f32_dpp v40, -v50, v0 row_newbcast:0 row_mask:0xf bank_mask:0xf
	v_fmac_f32_dpp v41, -v50, v1 row_newbcast:1 row_mask:0xf bank_mask:0xf
	v_fmac_f32_dpp v40, -v50, v2 row_newbcast:2 row_mask:0xf bank_mask:0xf
	v_fmac_f32_dpp v41, -v50, v3 row_newbcast:3 row_mask:0xf bank_mask:0xf
	v_fmac_f32_dpp v40, -v50, v4 row_newbcast:4 row_mask:0xf bank_mask:0xf
	v_fmac_f32_dpp v41, -v50, v5 row_newbcast:5 row_mask:0xf bank_mask:0xf
	v_fmac_f32_dpp v40, -v50, v6 row_newbcast:6 row_mask:0xf bank_mask:0xf
	v_fmac_f32_dpp v41, -v50, v7 row_newbcast:7 row_mask:0xf bank_mask:0xf
	v_fmac_f32_dpp v40, -v50, v8 row_newbcast:8 row_mask:0xf bank_mask:0xf
	v_fmac_f32_dpp v41, -v50, v9 row_newbcast:9 row_mask:0xf bank_mask:0xf
	v_fmac_f32_dpp v40, -v50, v10 row_newbcast:10 row_mask:0xf bank_mask:0xf
	v_fmac_f32_dpp v41, -v50, v11 row_newbcast:11 row_mask:0xf bank_mask:0xf
	v_fmac_f32_dpp v40, -v50, v12 row_newbcast:12 row_mask:0xf bank_mask:0xf
	v_fmac_f32_dpp v41, -v50, v13 row_newbcast:13 row_mask:0xf bank_mask:0xf
	v_fmac_f32_dpp v40, -v50, v14 row_newbcast:14 row_mask:0xf bank_mask:0xf
	v_fmac_f32_dpp v41, -v50, v15 row_newbcast:15 row_mask:0xf bank_mask:0xf
	v_fmac_f32_dpp v40, -v51, v16 row_newbcast:0 row_mask:0xf bank_mask:0xf
	ds_read_b32 v57, v38 offset:37888
	ds_read_b32 v50, v37 offset:9472
	ds_read_b32 v51, v37 offset:9600
	v_add_f32_e32 v42, v40, v41
	v_mov_b32_e32 v43, v42
	s_nop 1
	v_permlane32_swap_b32_e32 v42, v43
	s_nop 1
	v_add_f32_dpp v17, v42, v43 quad_perm:[0,1,2,3] row_mask:0x3 bank_mask:0xf
	s_waitcnt lgkmcnt(9)
; #define LAS __attribute__((address_space(3)))
; __device__ __forceinline__ void phase_chunk_prep(const Params& p, LAS unsigned char* lds, int wave_s) {
;     ...
;             for (int i = 0; i < 64; ++i) {
;                 float s0 = RHS[i * 256 + col], s1 = 0.f, s2 = 0.f, s3 = 0.f;
; #pragma unroll
;                 for (int j4 = 0; j4 < (i + 3) / 4; ++j4) { const f32x4 a = *(const LAS f32x4*)(AM + i * 64 + 4 * j4);
;                     s0 -= a.x * sol[4 * j4]; s1 -= a.y * sol[4 * j4 + 1]; s2 -= a.z * sol[4 * j4 + 2]; s3 -= a.w * sol[4 * j4 + 3]; }
;                 sol[i] = (s0 + s1) + (s2 + s3);
;             }
	v_mul_f32_e32 v40, v58, v39
	v_mov_b32_e32 v41, 0
	v_fmac_f32_dpp v40, -v52, v0 row_newbcast:0 row_mask:0xf bank_mask:0xf
	v_fmac_f32_dpp v41, -v52, v1 row_newbcast:1 row_mask:0xf bank_mask:0xf
	v_fmac_f32_dpp v40, -v52, v2 row_newbcast:2 row_mask:0xf bank_mask:0xf
	v_fmac_f32_dpp v41, -v52, v3 row_newbcast:3 row_mask:0xf bank_mask:0xf
	v_fmac_f32_dpp v40, -v52, v4 row_newbcast:4 row_mask:0xf bank_mask:0xf
	v_fmac_f32_dpp v41, -v52, v5 row_newbcast:5 row_mask:0xf bank_mask:0xf
	v_fmac_f32_dpp v40, -v52, v6 row_newbcast:6 row_mask:0xf bank_mask:0xf
	v_fmac_f32_dpp v41, -v52, v7 row_newbcast:7 row_mask:0xf bank_mask:0xf
	v_fmac_f32_dpp v40, -v52, v8 row_newbcast:8 row_mask:0xf bank_mask:0xf
	v_fmac_f32_dpp v41, -v52, v9 row_newbcast:9 row_mask:0xf bank_mask:0xf
	v_fmac_f32_dpp v40, -v52, v10 row_newbcast:10 row_mask:0xf bank_mask:0xf
	v_fmac_f32_dpp v41, -v52, v11 row_newbcast:11 row_mask:0xf bank_mask:0xf
	v_fmac_f32_dpp v40, -v52, v12 row_newbcast:12 row_mask:0xf bank_mask:0xf
	v_fmac_f32_dpp v41, -v52, v13 row_newbcast:13 row_mask:0xf bank_mask:0xf
	v_fmac_f32_dpp v40, -v52, v14 row_newbcast:14 row_mask:0xf bank_mask:0xf
	v_fmac_f32_dpp v41, -v52, v15 row_newbcast:15 row_mask:0xf bank_mask:0xf
	v_fmac_f32_dpp v40, -v53, v16 row_newbcast:0 row_mask:0xf bank_mask:0xf
	v_fmac_f32_dpp v41, -v53, v17 row_newbcast:1 row_mask:0xf bank_mask:0xf
	ds_read_b32 v58, v38 offset:38912
	ds_read_b32 v52, v37 offset:9728
	ds_read_b32 v53, v37 offset:9856
	v_add_f32_e32 v42, v40, v41
	v_mov_b32_e32 v43, v42
	s_nop 1
	v_permlane32_swap_b32_e32 v42, v43
	s_nop 1
	v_add_f32_dpp v16, v42, v43 quad_perm:[0,1,2,3] row_mask:0xc bank_mask:0xf
	s_waitcnt lgkmcnt(9)
	v_mul_f32_e32 v40, v59, v39
	v_mov_b32_e32 v41, 0
	v_fmac_f32_dpp v40, -v54, v0 row_newbcast:0 row_mask:0xf bank_mask:0xf
	v_fmac_f32_dpp v41, -v54, v1 row_newbcast:1 row_mask:0xf bank_mask:0xf
	v_fmac_f32_dpp v40, -v54, v2 row_newbcast:2 row_mask:0xf bank_mask:0xf
	v_fmac_f32_dpp v41, -v54, v3 row_newbcast:3 row_mask:0xf bank_mask:0xf
	v_fmac_f32_dpp v40, -v54, v4 row_newbcast:4 row_mask:0xf bank_mask:0xf
	v_fmac_f32_dpp v41, -v54, v5 row_newbcast:5 row_mask:0xf bank_mask:0xf
	v_fmac_f32_dpp v40, -v54, v6 row_newbcast:6 row_mask:0xf bank_mask:0xf
	v_fmac_f32_dpp v41, -v54, v7 row_newbcast:7 row_mask:0xf bank_mask:0xf
	v_fmac_f32_dpp v40, -v54, v8 row_newbcast:8 row_mask:0xf bank_mask:0xf
	v_fmac_f32_dpp v41, -v54, v9 row_newbcast:9 row_mask:0xf bank_mask:0xf
	v_fmac_f32_dpp v40, -v54, v10 row_newbcast:10 row_mask:0xf bank_mask:0xf
	v_fmac_f32_dpp v41, -v54, v11 row_newbcast:11 row_mask:0xf bank_mask:0xf
	v_fmac_f32_dpp v40, -v54, v12 row_newbcast:12 row_mask:0xf bank_mask:0xf
	v_fmac_f32_dpp v41, -v54, v13 row_newbcast:13 row_mask:0xf bank_mask:0xf
	v_fmac_f32_dpp v40, -v54, v14 row_newbcast:14 row_mask:0xf bank_mask:0xf
	v_fmac_f32_dpp v41, -v54, v15 row_newbcast:15 row_mask:0xf bank_mask:0xf
	v_fmac_f32_dpp v40, -v55, v16 row_newbcast:0 row_mask:0xf bank_mask:0xf
	v_fmac_f32_dpp v41, -v55, v17 row_newbcast:1 row_mask:0xf bank_mask:0xf
	ds_read_b32 v59, v38 offset:39936
	ds_read_b32 v54, v37 offset:9984
	ds_read_b32 v55, v37 offset:10112
	v_add_f32_e32 v42, v40, v41
	v_mov_b32_e32 v43, v42
	s_nop 1
	v_permlane32_swap_b32_e32 v42, v43
	s_nop 1
	v_add_f32_dpp v17, v42, v43 quad_perm:[0,1,2,3] row_mask:0xc bank_mask:0xf
	s_waitcnt lgkmcnt(9)
	v_mul_f32_e32 v40, v56, v39
	v_mov_b32_e32 v41, 0
	v_fmac_f32_dpp v40, -v48, v0 row_newbcast:0 row_mask:0xf bank_mask:0xf
	v_fmac_f32_dpp v41, -v48, v1 row_newbcast:1 row_mask:0xf bank_mask:0xf
	v_fmac_f32_dpp v40, -v48, v2 row_newbcast:2 row_mask:0xf bank_mask:0xf
	v_fmac_f32_dpp v41, -v48, v3 row_newbcast:3 row_mask:0xf bank_mask:0xf
	v_fmac_f32_dpp v40, -v48, v4 row_newbcast:4 row_mask:0xf bank_mask:0xf
	v_fmac_f32_dpp v41, -v48, v5 row_newbcast:5 row_mask:0xf bank_mask:0xf
	v_fmac_f32_dpp v40, -v48, v6 row_newbcast:6 row_mask:0xf bank_mask:0xf
	v_fmac_f32_dpp v41, -v48, v7 row_newbcast:7 row_mask:0xf bank_mask:0xf
	v_fmac_f32_dpp v40, -v48, v8 row_newbcast:8 row_mask:0xf bank_mask:0xf
	v_fmac_f32_dpp v41, -v48, v9 row_newbcast:9 row_mask:0xf bank_mask:0xf
	v_fmac_f32_dpp v40, -v48, v10 row_newbcast:10 row_mask:0xf bank_mask:0xf
	v_fmac_f32_dpp v41, -v48, v11 row_newbcast:11 row_mask:0xf bank_mask:0xf
	v_fmac_f32_dpp v40, -v48, v12 row_newbcast:12 row_mask:0xf bank_mask:0xf
	v_fmac_f32_dpp v41, -v48, v13 row_newbcast:13 row_mask:0xf bank_mask:0xf
	v_fmac_f32_dpp v40, -v48, v14 row_newbcast:14 row_mask:0xf bank_mask:0xf
	v_fmac_f32_dpp v41, -v48, v15 row_newbcast:15 row_mask:0xf bank_mask:0xf
	v_fmac_f32_dpp v40, -v49, v16 row_newbcast:0 row_mask:0xf bank_mask:0xf
	v_fmac_f32_dpp v41, -v49, v17 row_newbcast:1 row_mask:0xf bank_mask:0xf
	ds_read_b32 v56, v38 offset:40960
	ds_read_b32 v48, v37 offset:10240
	ds_read_b32 v49, v37 offset:10368
	v_add_f32_e32 v42, v40, v41
	v_mov_b32_e32 v43, v42
	s_nop 1
	v_permlane32_swap_b32_e32 v42, v43
	s_nop 1
	v_add_f32_dpp v18, v42, v43 quad_perm:[0,1,2,3] row_mask:0x3 bank_mask:0xf
	s_waitcnt lgkmcnt(9)
; #define LAS __attribute__((address_space(3)))
; __device__ __forceinline__ void phase_chunk_prep(const Params& p, LAS unsigned char* lds, int wave_s) {
;     ...
;             for (int i = 0; i < 64; ++i) {
;                 float s0 = RHS[i * 256 + col], s1 = 0.f, s2 = 0.f, s3 = 0.f;
; #pragma unroll
;                 for (int j4 = 0; j4 < (i + 3) / 4; ++j4) { const f32x4 a = *(const LAS f32x4*)(AM + i * 64 + 4 * j4);
;                     s0 -= a.x * sol[4 * j4]; s1 -= a.y * sol[4 * j4 + 1]; s2 -= a.z * sol[4 * j4 + 2]; s3 -= a.w * sol[4 * j4 + 3]; }
;                 sol[i] = (s0 + s1) + (s2 + s3);
;             }
	v_mul_f32_e32 v40, v57, v39
	v_mov_b32_e32 v41, 0
	v_fmac_f32_dpp v40, -v50, v0 row_newbcast:0 row_mask:0xf bank_mask:0xf
	v_fmac_f32_dpp v41, -v50, v1 row_newbcast:1 row_mask:0xf bank_mask:0xf
	v_fmac_f32_dpp v40, -v50, v2 row_newbcast:2 row_mask:0xf bank_mask:0xf
	v_fmac_f32_dpp v41, -v50, v3 row_newbcast:3 row_mask:0xf bank_mask:0xf
	v_fmac_f32_dpp v40, -v50, v4 row_newbcast:4 row_mask:0xf bank_mask:0xf
	v_fmac_f32_dpp v41, -v50, v5 row_newbcast:5 row_mask:0xf bank_mask:0xf
	v_fmac_f32_dpp v40, -v50, v6 row_newbcast:6 row_mask:0xf bank_mask:0xf
	v_fmac_f32_dpp v41, -v50, v7 row_newbcast:7 row_mask:0xf bank_mask:0xf
	v_fmac_f32_dpp v40, -v50, v8 row_newbcast:8 row_mask:0xf bank_mask:0xf
	v_fmac_f32_dpp v41, -v50, v9 row_newbcast:9 row_mask:0xf bank_mask:0xf
	v_fmac_f32_dpp v40, -v50, v10 row_newbcast:10 row_mask:0xf bank_mask:0xf
	v_fmac_f32_dpp v41, -v50, v11 row_newbcast:11 row_mask:0xf bank_mask:0xf
	v_fmac_f32_dpp v40, -v50, v12 row_newbcast:12 row_mask:0xf bank_mask:0xf
	v_fmac_f32_dpp v41, -v50, v13 row_newbcast:13 row_mask:0xf bank_mask:0xf
	v_fmac_f32_dpp v40, -v50, v14 row_newbcast:14 row_mask:0xf bank_mask:0xf
	v_fmac_f32_dpp v41, -v50, v15 row_newbcast:15 row_mask:0xf bank_mask:0xf
	v_fmac_f32_dpp v40, -v51, v16 row_newbcast:0 row_mask:0xf bank_mask:0xf
	v_fmac_f32_dpp v41, -v51, v17 row_newbcast:1 row_mask:0xf bank_mask:0xf
	v_fmac_f32_dpp v40, -v51, v18 row_newbcast:2 row_mask:0xf bank_mask:0xf
	ds_read_b32 v57, v38 offset:41984
	ds_read_b32 v50, v37 offset:10496
	ds_read_b32 v51, v37 offset:10624
	v_add_f32_e32 v42, v40, v41
	v_mov_b32_e32 v43, v42
	s_nop 1
	v_permlane32_swap_b32_e32 v42, v43
	s_nop 1
	v_add_f32_dpp v19, v42, v43 quad_perm:[0,1,2,3] row_mask:0x3 bank_mask:0xf
	s_waitcnt lgkmcnt(9)
	v_mul_f32_e32 v40, v58, v39
	v_mov_b32_e32 v41, 0
	v_fmac_f32_dpp v40, -v52, v0 row_newbcast:0 row_mask:0xf bank_mask:0xf
	v_fmac_f32_dpp v41, -v52, v1 row_newbcast:1 row_mask:0xf bank_mask:0xf
	v_fmac_f32_dpp v40, -v52, v2 row_newbcast:2 row_mask:0xf bank_mask:0xf
	v_fmac_f32_dpp v41, -v52, v3 row_newbcast:3 row_mask:0xf bank_mask:0xf
	v_fmac_f32_dpp v40, -v52, v4 row_newbcast:4 row_mask:0xf bank_mask:0xf
	v_fmac_f32_dpp v41, -v52, v5 row_newbcast:5 row_mask:0xf bank_mask:0xf
	v_fmac_f32_dpp v40, -v52, v6 row_newbcast:6 row_mask:0xf bank_mask:0xf
	v_fmac_f32_dpp v41, -v52, v7 row_newbcast:7 row_mask:0xf bank_mask:0xf
	v_fmac_f32_dpp v40, -v52, v8 row_newbcast:8 row_mask:0xf bank_mask:0xf
	v_fmac_f32_dpp v41, -v52, v9 row_newbcast:9 row_mask:0xf bank_mask:0xf
	v_fmac_f32_dpp v40, -v52, v10 row_newbcast:10 row_mask:0xf bank_mask:0xf
	v_fmac_f32_dpp v41, -v52, v11 row_newbcast:11 row_mask:0xf bank_mask:0xf
	v_fmac_f32_dpp v40, -v52, v12 row_newbcast:12 row_mask:0xf bank_mask:0xf
	v_fmac_f32_dpp v41, -v52, v13 row_newbcast:13 row_mask:0xf bank_mask:0xf
	v_fmac_f32_dpp v40, -v52, v14 row_newbcast:14 row_mask:0xf bank_mask:0xf
	v_fmac_f32_dpp v41, -v52, v15 row_newbcast:15 row_mask:0xf bank_mask:0xf
	v_fmac_f32_dpp v40, -v53, v16 row_newbcast:0 row_mask:0xf bank_mask:0xf
	v_fmac_f32_dpp v41, -v53, v17 row_newbcast:1 row_mask:0xf bank_mask:0xf
	v_fmac_f32_dpp v40, -v53, v18 row_newbcast:2 row_mask:0xf bank_mask:0xf
	v_fmac_f32_dpp v41, -v53, v19 row_newbcast:3 row_mask:0xf bank_mask:0xf
	ds_read_b32 v58, v38 offset:43008
	ds_read_b32 v52, v37 offset:10752
	ds_read_b32 v53, v37 offset:10880
	v_add_f32_e32 v42, v40, v41
	v_mov_b32_e32 v43, v42
	s_nop 1
	v_permlane32_swap_b32_e32 v42, v43
	s_nop 1
	v_add_f32_dpp v18, v42, v43 quad_perm:[0,1,2,3] row_mask:0xc bank_mask:0xf
	s_waitcnt lgkmcnt(9)
	v_mul_f32_e32 v40, v59, v39
	v_mov_b32_e32 v41, 0
	v_fmac_f32_dpp v40, -v54, v0 row_newbcast:0 row_mask:0xf bank_mask:0xf
	v_fmac_f32_dpp v41, -v54, v1 row_newbcast:1 row_mask:0xf bank_mask:0xf
	v_fmac_f32_dpp v40, -v54, v2 row_newbcast:2 row_mask:0xf bank_mask:0xf
	v_fmac_f32_dpp v41, -v54, v3 row_newbcast:3 row_mask:0xf bank_mask:0xf
	v_fmac_f32_dpp v40, -v54, v4 row_newbcast:4 row_mask:0xf bank_mask:0xf
	v_fmac_f32_dpp v41, -v54, v5 row_newbcast:5 row_mask:0xf bank_mask:0xf
	v_fmac_f32_dpp v40, -v54, v6 row_newbcast:6 row_mask:0xf bank_mask:0xf
	v_fmac_f32_dpp v41, -v54, v7 row_newbcast:7 row_mask:0xf bank_mask:0xf
	v_fmac_f32_dpp v40, -v54, v8 row_newbcast:8 row_mask:0xf bank_mask:0xf
	v_fmac_f32_dpp v41, -v54, v9 row_newbcast:9 row_mask:0xf bank_mask:0xf
	v_fmac_f32_dpp v40, -v54, v10 row_newbcast:10 row_mask:0xf bank_mask:0xf
	v_fmac_f32_dpp v41, -v54, v11 row_newbcast:11 row_mask:0xf bank_mask:0xf
	v_fmac_f32_dpp v40, -v54, v12 row_newbcast:12 row_mask:0xf bank_mask:0xf
	v_fmac_f32_dpp v41, -v54, v13 row_newbcast:13 row_mask:0xf bank_mask:0xf
	v_fmac_f32_dpp v40, -v54, v14 row_newbcast:14 row_mask:0xf bank_mask:0xf
	v_fmac_f32_dpp v41, -v54, v15 row_newbcast:15 row_mask:0xf bank_mask:0xf
	v_fmac_f32_dpp v40, -v55, v16 row_newbcast:0 row_mask:0xf bank_mask:0xf
	v_fmac_f32_dpp v41, -v55, v17 row_newbcast:1 row_mask:0xf bank_mask:0xf
	v_fmac_f32_dpp v40, -v55, v18 row_newbcast:2 row_mask:0xf bank_mask:0xf
	v_fmac_f32_dpp v41, -v55, v19 row_newbcast:3 row_mask:0xf bank_mask:0xf
	ds_read_b32 v59, v38 offset:44032
	ds_read_b32 v54, v37 offset:11008
	ds_read_b32 v55, v37 offset:11136
	v_add_f32_e32 v42, v40, v41
	v_mov_b32_e32 v43, v42
	s_nop 1
	v_permlane32_swap_b32_e32 v42, v43
	s_nop 1
	v_add_f32_dpp v19, v42, v43 quad_perm:[0,1,2,3] row_mask:0xc bank_mask:0xf
	s_waitcnt lgkmcnt(9)
; #define LAS __attribute__((address_space(3)))
; __device__ __forceinline__ void phase_chunk_prep(const Params& p, LAS unsigned char* lds, int wave_s) {
;     ...
;             for (int i = 0; i < 64; ++i) {
;                 float s0 = RHS[i * 256 + col], s1 = 0.f, s2 = 0.f, s3 = 0.f;
; #pragma unroll
;                 for (int j4 = 0; j4 < (i + 3) / 4; ++j4) { const f32x4 a = *(const LAS f32x4*)(AM + i * 64 + 4 * j4);
;                     s0 -= a.x * sol[4 * j4]; s1 -= a.y * sol[4 * j4 + 1]; s2 -= a.z * sol[4 * j4 + 2]; s3 -= a.w * sol[4 * j4 + 3]; }
;                 sol[i] = (s0 + s1) + (s2 + s3);
;             }
	v_mul_f32_e32 v40, v56, v39
	v_mov_b32_e32 v41, 0
	v_fmac_f32_dpp v40, -v48, v0 row_newbcast:0 row_mask:0xf bank_mask:0xf
	v_fmac_f32_dpp v41, -v48, v1 row_newbcast:1 row_mask:0xf bank_mask:0xf
	v_fmac_f32_dpp v40, -v48, v2 row_newbcast:2 row_mask:0xf bank_mask:0xf
	v_fmac_f32_dpp v41, -v48, v3 row_newbcast:3 row_mask:0xf bank_mask:0xf
	v_fmac_f32_dpp v40, -v48, v4 row_newbcast:4 row_mask:0xf bank_mask:0xf
	v_fmac_f32_dpp v41, -v48, v5 row_newbcast:5 row_mask:0xf bank_mask:0xf
	v_fmac_f32_dpp v40, -v48, v6 row_newbcast:6 row_mask:0xf bank_mask:0xf
	v_fmac_f32_dpp v41, -v48, v7 row_newbcast:7 row_mask:0xf bank_mask:0xf
	v_fmac_f32_dpp v40, -v48, v8 row_newbcast:8 row_mask:0xf bank_mask:0xf
	v_fmac_f32_dpp v41, -v48, v9 row_newbcast:9 row_mask:0xf bank_mask:0xf
	v_fmac_f32_dpp v40, -v48, v10 row_newbcast:10 row_mask:0xf bank_mask:0xf
	v_fmac_f32_dpp v41, -v48, v11 row_newbcast:11 row_mask:0xf bank_mask:0xf
	v_fmac_f32_dpp v40, -v48, v12 row_newbcast:12 row_mask:0xf bank_mask:0xf
	v_fmac_f32_dpp v41, -v48, v13 row_newbcast:13 row_mask:0xf bank_mask:0xf
	v_fmac_f32_dpp v40, -v48, v14 row_newbcast:14 row_mask:0xf bank_mask:0xf
	v_fmac_f32_dpp v41, -v48, v15 row_newbcast:15 row_mask:0xf bank_mask:0xf
	v_fmac_f32_dpp v40, -v49, v16 row_newbcast:0 row_mask:0xf bank_mask:0xf
	v_fmac_f32_dpp v41, -v49, v17 row_newbcast:1 row_mask:0xf bank_mask:0xf
	v_fmac_f32_dpp v40, -v49, v18 row_newbcast:2 row_mask:0xf bank_mask:0xf
	v_fmac_f32_dpp v41, -v49, v19 row_newbcast:3 row_mask:0xf bank_mask:0xf
	ds_read_b32 v56, v38 offset:45056
	ds_read_b32 v48, v37 offset:11264
	ds_read_b32 v49, v37 offset:11392
	v_add_f32_e32 v42, v40, v41
	v_mov_b32_e32 v43, v42
	s_nop 1
	v_permlane32_swap_b32_e32 v42, v43
	s_nop 1
	v_add_f32_dpp v20, v42, v43 quad_perm:[0,1,2,3] row_mask:0x3 bank_mask:0xf
	s_waitcnt lgkmcnt(9)
	v_mul_f32_e32 v40, v57, v39
	v_mov_b32_e32 v41, 0
	v_fmac_f32_dpp v40, -v50, v0 row_newbcast:0 row_mask:0xf bank_mask:0xf
	v_fmac_f32_dpp v41, -v50, v1 row_newbcast:1 row_mask:0xf bank_mask:0xf
	v_fmac_f32_dpp v40, -v50, v2 row_newbcast:2 row_mask:0xf bank_mask:0xf
	v_fmac_f32_dpp v41, -v50, v3 row_newbcast:3 row_mask:0xf bank_mask:0xf
	v_fmac_f32_dpp v40, -v50, v4 row_newbcast:4 row_mask:0xf bank_mask:0xf
	v_fmac_f32_dpp v41, -v50, v5 row_newbcast:5 row_mask:0xf bank_mask:0xf
	v_fmac_f32_dpp v40, -v50, v6 row_newbcast:6 row_mask:0xf bank_mask:0xf
	v_fmac_f32_dpp v41, -v50, v7 row_newbcast:7 row_mask:0xf bank_mask:0xf
	v_fmac_f32_dpp v40, -v50, v8 row_newbcast:8 row_mask:0xf bank_mask:0xf
	v_fmac_f32_dpp v41, -v50, v9 row_newbcast:9 row_mask:0xf bank_mask:0xf
	v_fmac_f32_dpp v40, -v50, v10 row_newbcast:10 row_mask:0xf bank_mask:0xf
	v_fmac_f32_dpp v41, -v50, v11 row_newbcast:11 row_mask:0xf bank_mask:0xf
	v_fmac_f32_dpp v40, -v50, v12 row_newbcast:12 row_mask:0xf bank_mask:0xf
	v_fmac_f32_dpp v41, -v50, v13 row_newbcast:13 row_mask:0xf bank_mask:0xf
	v_fmac_f32_dpp v40, -v50, v14 row_newbcast:14 row_mask:0xf bank_mask:0xf
	v_fmac_f32_dpp v41, -v50, v15 row_newbcast:15 row_mask:0xf bank_mask:0xf
	v_fmac_f32_dpp v40, -v51, v16 row_newbcast:0 row_mask:0xf bank_mask:0xf
	v_fmac_f32_dpp v41, -v51, v17 row_newbcast:1 row_mask:0xf bank_mask:0xf
	v_fmac_f32_dpp v40, -v51, v18 row_newbcast:2 row_mask:0xf bank_mask:0xf
	v_fmac_f32_dpp v41, -v51, v19 row_newbcast:3 row_mask:0xf bank_mask:0xf
	v_fmac_f32_dpp v40, -v51, v20 row_newbcast:4 row_mask:0xf bank_mask:0xf
	ds_read_b32 v57, v38 offset:46080
	ds_read_b32 v50, v37 offset:11520
	ds_read_b32 v51, v37 offset:11648
	v_add_f32_e32 v42, v40, v41
	v_mov_b32_e32 v43, v42
	s_nop 1
	v_permlane32_swap_b32_e32 v42, v43
	s_nop 1
	v_add_f32_dpp v21, v42, v43 quad_perm:[0,1,2,3] row_mask:0x3 bank_mask:0xf
	s_waitcnt lgkmcnt(9)
	v_mul_f32_e32 v40, v58, v39
	v_mov_b32_e32 v41, 0
	v_fmac_f32_dpp v40, -v52, v0 row_newbcast:0 row_mask:0xf bank_mask:0xf
	v_fmac_f32_dpp v41, -v52, v1 row_newbcast:1 row_mask:0xf bank_mask:0xf
	v_fmac_f32_dpp v40, -v52, v2 row_newbcast:2 row_mask:0xf bank_mask:0xf
	v_fmac_f32_dpp v41, -v52, v3 row_newbcast:3 row_mask:0xf bank_mask:0xf
	v_fmac_f32_dpp v40, -v52, v4 row_newbcast:4 row_mask:0xf bank_mask:0xf
	v_fmac_f32_dpp v41, -v52, v5 row_newbcast:5 row_mask:0xf bank_mask:0xf
	v_fmac_f32_dpp v40, -v52, v6 row_newbcast:6 row_mask:0xf bank_mask:0xf
	v_fmac_f32_dpp v41, -v52, v7 row_newbcast:7 row_mask:0xf bank_mask:0xf
	v_fmac_f32_dpp v40, -v52, v8 row_newbcast:8 row_mask:0xf bank_mask:0xf
	v_fmac_f32_dpp v41, -v52, v9 row_newbcast:9 row_mask:0xf bank_mask:0xf
	v_fmac_f32_dpp v40, -v52, v10 row_newbcast:10 row_mask:0xf bank_mask:0xf
	v_fmac_f32_dpp v41, -v52, v11 row_newbcast:11 row_mask:0xf bank_mask:0xf
	v_fmac_f32_dpp v40, -v52, v12 row_newbcast:12 row_mask:0xf bank_mask:0xf
	v_fmac_f32_dpp v41, -v52, v13 row_newbcast:13 row_mask:0xf bank_mask:0xf
	v_fmac_f32_dpp v40, -v52, v14 row_newbcast:14 row_mask:0xf bank_mask:0xf
	v_fmac_f32_dpp v41, -v52, v15 row_newbcast:15 row_mask:0xf bank_mask:0xf
	v_fmac_f32_dpp v40, -v53, v16 row_newbcast:0 row_mask:0xf bank_mask:0xf
	v_fmac_f32_dpp v41, -v53, v17 row_newbcast:1 row_mask:0xf bank_mask:0xf
	v_fmac_f32_dpp v40, -v53, v18 row_newbcast:2 row_mask:0xf bank_mask:0xf
	v_fmac_f32_dpp v41, -v53, v19 row_newbcast:3 row_mask:0xf bank_mask:0xf
	v_fmac_f32_dpp v40, -v53, v20 row_newbcast:4 row_mask:0xf bank_mask:0xf
	v_fmac_f32_dpp v41, -v53, v21 row_newbcast:5 row_mask:0xf bank_mask:0xf
	ds_read_b32 v58, v38 offset:47104
	ds_read_b32 v52, v37 offset:11776
	ds_read_b32 v53, v37 offset:11904
	v_add_f32_e32 v42, v40, v41
	v_mov_b32_e32 v43, v42
	s_nop 1
	v_permlane32_swap_b32_e32 v42, v43
	s_nop 1
	v_add_f32_dpp v20, v42, v43 quad_perm:[0,1,2,3] row_mask:0xc bank_mask:0xf
	s_waitcnt lgkmcnt(9)
; #define LAS __attribute__((address_space(3)))
; __device__ __forceinline__ void phase_chunk_prep(const Params& p, LAS unsigned char* lds, int wave_s) {
;     ...
;             for (int i = 0; i < 64; ++i) {
;                 float s0 = RHS[i * 256 + col], s1 = 0.f, s2 = 0.f, s3 = 0.f;
; #pragma unroll
;                 for (int j4 = 0; j4 < (i + 3) / 4; ++j4) { const f32x4 a = *(const LAS f32x4*)(AM + i * 64 + 4 * j4);
;                     s0 -= a.x * sol[4 * j4]; s1 -= a.y * sol[4 * j4 + 1]; s2 -= a.z * sol[4 * j4 + 2]; s3 -= a.w * sol[4 * j4 + 3]; }
;                 sol[i] = (s0 + s1) + (s2 + s3);
;             }
	v_mul_f32_e32 v40, v59, v39
	v_mov_b32_e32 v41, 0
	v_fmac_f32_dpp v40, -v54, v0 row_newbcast:0 row_mask:0xf bank_mask:0xf
	v_fmac_f32_dpp v41, -v54, v1 row_newbcast:1 row_mask:0xf bank_mask:0xf
	v_fmac_f32_dpp v40, -v54, v2 row_newbcast:2 row_mask:0xf bank_mask:0xf
	v_fmac_f32_dpp v41, -v54, v3 row_newbcast:3 row_mask:0xf bank_mask:0xf
	v_fmac_f32_dpp v40, -v54, v4 row_newbcast:4 row_mask:0xf bank_mask:0xf
	v_fmac_f32_dpp v41, -v54, v5 row_newbcast:5 row_mask:0xf bank_mask:0xf
	v_fmac_f32_dpp v40, -v54, v6 row_newbcast:6 row_mask:0xf bank_mask:0xf
	v_fmac_f32_dpp v41, -v54, v7 row_newbcast:7 row_mask:0xf bank_mask:0xf
	v_fmac_f32_dpp v40, -v54, v8 row_newbcast:8 row_mask:0xf bank_mask:0xf
	v_fmac_f32_dpp v41, -v54, v9 row_newbcast:9 row_mask:0xf bank_mask:0xf
	v_fmac_f32_dpp v40, -v54, v10 row_newbcast:10 row_mask:0xf bank_mask:0xf
	v_fmac_f32_dpp v41, -v54, v11 row_newbcast:11 row_mask:0xf bank_mask:0xf
	v_fmac_f32_dpp v40, -v54, v12 row_newbcast:12 row_mask:0xf bank_mask:0xf
	v_fmac_f32_dpp v41, -v54, v13 row_newbcast:13 row_mask:0xf bank_mask:0xf
	v_fmac_f32_dpp v40, -v54, v14 row_newbcast:14 row_mask:0xf bank_mask:0xf
	v_fmac_f32_dpp v41, -v54, v15 row_newbcast:15 row_mask:0xf bank_mask:0xf
	v_fmac_f32_dpp v40, -v55, v16 row_newbcast:0 row_mask:0xf bank_mask:0xf
	v_fmac_f32_dpp v41, -v55, v17 row_newbcast:1 row_mask:0xf bank_mask:0xf
	v_fmac_f32_dpp v40, -v55, v18 row_newbcast:2 row_mask:0xf bank_mask:0xf
	v_fmac_f32_dpp v41, -v55, v19 row_newbcast:3 row_mask:0xf bank_mask:0xf
	v_fmac_f32_dpp v40, -v55, v20 row_newbcast:4 row_mask:0xf bank_mask:0xf
	v_fmac_f32_dpp v41, -v55, v21 row_newbcast:5 row_mask:0xf bank_mask:0xf
	ds_read_b32 v59, v38 offset:48128
	ds_read_b32 v54, v37 offset:12032
	ds_read_b32 v55, v37 offset:12160
	v_add_f32_e32 v42, v40, v41
	v_mov_b32_e32 v43, v42
	s_nop 1
	v_permlane32_swap_b32_e32 v42, v43
	s_nop 1
	v_add_f32_dpp v21, v42, v43 quad_perm:[0,1,2,3] row_mask:0xc bank_mask:0xf
	s_waitcnt lgkmcnt(9)
	v_mul_f32_e32 v40, v56, v39
	v_mov_b32_e32 v41, 0
	v_fmac_f32_dpp v40, -v48, v0 row_newbcast:0 row_mask:0xf bank_mask:0xf
	v_fmac_f32_dpp v41, -v48, v1 row_newbcast:1 row_mask:0xf bank_mask:0xf
	v_fmac_f32_dpp v40, -v48, v2 row_newbcast:2 row_mask:0xf bank_mask:0xf
	v_fmac_f32_dpp v41, -v48, v3 row_newbcast:3 row_mask:0xf bank_mask:0xf
	v_fmac_f32_dpp v40, -v48, v4 row_newbcast:4 row_mask:0xf bank_mask:0xf
	v_fmac_f32_dpp v41, -v48, v5 row_newbcast:5 row_mask:0xf bank_mask:0xf
	v_fmac_f32_dpp v40, -v48, v6 row_newbcast:6 row_mask:0xf bank_mask:0xf
	v_fmac_f32_dpp v41, -v48, v7 row_newbcast:7 row_mask:0xf bank_mask:0xf
	v_fmac_f32_dpp v40, -v48, v8 row_newbcast:8 row_mask:0xf bank_mask:0xf
	v_fmac_f32_dpp v41, -v48, v9 row_newbcast:9 row_mask:0xf bank_mask:0xf
	v_fmac_f32_dpp v40, -v48, v10 row_newbcast:10 row_mask:0xf bank_mask:0xf
	v_fmac_f32_dpp v41, -v48, v11 row_newbcast:11 row_mask:0xf bank_mask:0xf
	v_fmac_f32_dpp v40, -v48, v12 row_newbcast:12 row_mask:0xf bank_mask:0xf
	v_fmac_f32_dpp v41, -v48, v13 row_newbcast:13 row_mask:0xf bank_mask:0xf
	v_fmac_f32_dpp v40, -v48, v14 row_newbcast:14 row_mask:0xf bank_mask:0xf
	v_fmac_f32_dpp v41, -v48, v15 row_newbcast:15 row_mask:0xf bank_mask:0xf
	v_fmac_f32_dpp v40, -v49, v16 row_newbcast:0 row_mask:0xf bank_mask:0xf
	v_fmac_f32_dpp v41, -v49, v17 row_newbcast:1 row_mask:0xf bank_mask:0xf
	v_fmac_f32_dpp v40, -v49, v18 row_newbcast:2 row_mask:0xf bank_mask:0xf
	v_fmac_f32_dpp v41, -v49, v19 row_newbcast:3 row_mask:0xf bank_mask:0xf
	v_fmac_f32_dpp v40, -v49, v20 row_newbcast:4 row_mask:0xf bank_mask:0xf
	v_fmac_f32_dpp v41, -v49, v21 row_newbcast:5 row_mask:0xf bank_mask:0xf
	ds_read_b32 v56, v38 offset:49152
	ds_read_b32 v48, v37 offset:12288
	ds_read_b32 v49, v37 offset:12416
	v_add_f32_e32 v42, v40, v41
	v_mov_b32_e32 v43, v42
	s_nop 1
	v_permlane32_swap_b32_e32 v42, v43
	s_nop 1
	v_add_f32_dpp v22, v42, v43 quad_perm:[0,1,2,3] row_mask:0x3 bank_mask:0xf
	s_waitcnt lgkmcnt(9)
	v_mul_f32_e32 v40, v57, v39
	v_mov_b32_e32 v41, 0
	v_fmac_f32_dpp v40, -v50, v0 row_newbcast:0 row_mask:0xf bank_mask:0xf
	v_fmac_f32_dpp v41, -v50, v1 row_newbcast:1 row_mask:0xf bank_mask:0xf
	v_fmac_f32_dpp v40, -v50, v2 row_newbcast:2 row_mask:0xf bank_mask:0xf
	v_fmac_f32_dpp v41, -v50, v3 row_newbcast:3 row_mask:0xf bank_mask:0xf
	v_fmac_f32_dpp v40, -v50, v4 row_newbcast:4 row_mask:0xf bank_mask:0xf
	v_fmac_f32_dpp v41, -v50, v5 row_newbcast:5 row_mask:0xf bank_mask:0xf
	v_fmac_f32_dpp v40, -v50, v6 row_newbcast:6 row_mask:0xf bank_mask:0xf
	v_fmac_f32_dpp v41, -v50, v7 row_newbcast:7 row_mask:0xf bank_mask:0xf
	v_fmac_f32_dpp v40, -v50, v8 row_newbcast:8 row_mask:0xf bank_mask:0xf
	v_fmac_f32_dpp v41, -v50, v9 row_newbcast:9 row_mask:0xf bank_mask:0xf
	v_fmac_f32_dpp v40, -v50, v10 row_newbcast:10 row_mask:0xf bank_mask:0xf
	v_fmac_f32_dpp v41, -v50, v11 row_newbcast:11 row_mask:0xf bank_mask:0xf
	v_fmac_f32_dpp v40, -v50, v12 row_newbcast:12 row_mask:0xf bank_mask:0xf
	v_fmac_f32_dpp v41, -v50, v13 row_newbcast:13 row_mask:0xf bank_mask:0xf
	v_fmac_f32_dpp v40, -v50, v14 row_newbcast:14 row_mask:0xf bank_mask:0xf
	v_fmac_f32_dpp v41, -v50, v15 row_newbcast:15 row_mask:0xf bank_mask:0xf
	v_fmac_f32_dpp v40, -v51, v16 row_newbcast:0 row_mask:0xf bank_mask:0xf
	v_fmac_f32_dpp v41, -v51, v17 row_newbcast:1 row_mask:0xf bank_mask:0xf
	v_fmac_f32_dpp v40, -v51, v18 row_newbcast:2 row_mask:0xf bank_mask:0xf
	v_fmac_f32_dpp v41, -v51, v19 row_newbcast:3 row_mask:0xf bank_mask:0xf
	v_fmac_f32_dpp v40, -v51, v20 row_newbcast:4 row_mask:0xf bank_mask:0xf
	v_fmac_f32_dpp v41, -v51, v21 row_newbcast:5 row_mask:0xf bank_mask:0xf
	v_fmac_f32_dpp v40, -v51, v22 row_newbcast:6 row_mask:0xf bank_mask:0xf
	ds_read_b32 v57, v38 offset:50176
	ds_read_b32 v50, v37 offset:12544
	ds_read_b32 v51, v37 offset:12672
	v_add_f32_e32 v42, v40, v41
	v_mov_b32_e32 v43, v42
	s_nop 1
	v_permlane32_swap_b32_e32 v42, v43
	s_nop 1
	v_add_f32_dpp v23, v42, v43 quad_perm:[0,1,2,3] row_mask:0x3 bank_mask:0xf
	s_waitcnt lgkmcnt(9)
; #define LAS __attribute__((address_space(3)))
; __device__ __forceinline__ void phase_chunk_prep(const Params& p, LAS unsigned char* lds, int wave_s) {
;     ...
;             for (int i = 0; i < 64; ++i) {
;                 float s0 = RHS[i * 256 + col], s1 = 0.f, s2 = 0.f, s3 = 0.f;
; #pragma unroll
;                 for (int j4 = 0; j4 < (i + 3) / 4; ++j4) { const f32x4 a = *(const LAS f32x4*)(AM + i * 64 + 4 * j4);
;                     s0 -= a.x * sol[4 * j4]; s1 -= a.y * sol[4 * j4 + 1]; s2 -= a.z * sol[4 * j4 + 2]; s3 -= a.w * sol[4 * j4 + 3]; }
;                 sol[i] = (s0 + s1) + (s2 + s3);
;             }
	v_mul_f32_e32 v40, v58, v39
	v_mov_b32_e32 v41, 0
	v_fmac_f32_dpp v40, -v52, v0 row_newbcast:0 row_mask:0xf bank_mask:0xf
	v_fmac_f32_dpp v41, -v52, v1 row_newbcast:1 row_mask:0xf bank_mask:0xf
	v_fmac_f32_dpp v40, -v52, v2 row_newbcast:2 row_mask:0xf bank_mask:0xf
	v_fmac_f32_dpp v41, -v52, v3 row_newbcast:3 row_mask:0xf bank_mask:0xf
	v_fmac_f32_dpp v40, -v52, v4 row_newbcast:4 row_mask:0xf bank_mask:0xf
	v_fmac_f32_dpp v41, -v52, v5 row_newbcast:5 row_mask:0xf bank_mask:0xf
	v_fmac_f32_dpp v40, -v52, v6 row_newbcast:6 row_mask:0xf bank_mask:0xf
	v_fmac_f32_dpp v41, -v52, v7 row_newbcast:7 row_mask:0xf bank_mask:0xf
	v_fmac_f32_dpp v40, -v52, v8 row_newbcast:8 row_mask:0xf bank_mask:0xf
	v_fmac_f32_dpp v41, -v52, v9 row_newbcast:9 row_mask:0xf bank_mask:0xf
	v_fmac_f32_dpp v40, -v52, v10 row_newbcast:10 row_mask:0xf bank_mask:0xf
	v_fmac_f32_dpp v41, -v52, v11 row_newbcast:11 row_mask:0xf bank_mask:0xf
	v_fmac_f32_dpp v40, -v52, v12 row_newbcast:12 row_mask:0xf bank_mask:0xf
	v_fmac_f32_dpp v41, -v52, v13 row_newbcast:13 row_mask:0xf bank_mask:0xf
	v_fmac_f32_dpp v40, -v52, v14 row_newbcast:14 row_mask:0xf bank_mask:0xf
	v_fmac_f32_dpp v41, -v52, v15 row_newbcast:15 row_mask:0xf bank_mask:0xf
	v_fmac_f32_dpp v40, -v53, v16 row_newbcast:0 row_mask:0xf bank_mask:0xf
	v_fmac_f32_dpp v41, -v53, v17 row_newbcast:1 row_mask:0xf bank_mask:0xf
	v_fmac_f32_dpp v40, -v53, v18 row_newbcast:2 row_mask:0xf bank_mask:0xf
	v_fmac_f32_dpp v41, -v53, v19 row_newbcast:3 row_mask:0xf bank_mask:0xf
	v_fmac_f32_dpp v40, -v53, v20 row_newbcast:4 row_mask:0xf bank_mask:0xf
	v_fmac_f32_dpp v41, -v53, v21 row_newbcast:5 row_mask:0xf bank_mask:0xf
	v_fmac_f32_dpp v40, -v53, v22 row_newbcast:6 row_mask:0xf bank_mask:0xf
	v_fmac_f32_dpp v41, -v53, v23 row_newbcast:7 row_mask:0xf bank_mask:0xf
	ds_read_b32 v58, v38 offset:51200
	ds_read_b32 v52, v37 offset:12800
	ds_read_b32 v53, v37 offset:12928
	v_add_f32_e32 v42, v40, v41
	v_mov_b32_e32 v43, v42
	s_nop 1
	v_permlane32_swap_b32_e32 v42, v43
	s_nop 1
	v_add_f32_dpp v22, v42, v43 quad_perm:[0,1,2,3] row_mask:0xc bank_mask:0xf
	s_waitcnt lgkmcnt(9)
	v_mul_f32_e32 v40, v59, v39
	v_mov_b32_e32 v41, 0
	v_fmac_f32_dpp v40, -v54, v0 row_newbcast:0 row_mask:0xf bank_mask:0xf
	v_fmac_f32_dpp v41, -v54, v1 row_newbcast:1 row_mask:0xf bank_mask:0xf
	v_fmac_f32_dpp v40, -v54, v2 row_newbcast:2 row_mask:0xf bank_mask:0xf
	v_fmac_f32_dpp v41, -v54, v3 row_newbcast:3 row_mask:0xf bank_mask:0xf
	v_fmac_f32_dpp v40, -v54, v4 row_newbcast:4 row_mask:0xf bank_mask:0xf
	v_fmac_f32_dpp v41, -v54, v5 row_newbcast:5 row_mask:0xf bank_mask:0xf
	v_fmac_f32_dpp v40, -v54, v6 row_newbcast:6 row_mask:0xf bank_mask:0xf
	v_fmac_f32_dpp v41, -v54, v7 row_newbcast:7 row_mask:0xf bank_mask:0xf
	v_fmac_f32_dpp v40, -v54, v8 row_newbcast:8 row_mask:0xf bank_mask:0xf
	v_fmac_f32_dpp v41, -v54, v9 row_newbcast:9 row_mask:0xf bank_mask:0xf
	v_fmac_f32_dpp v40, -v54, v10 row_newbcast:10 row_mask:0xf bank_mask:0xf
	v_fmac_f32_dpp v41, -v54, v11 row_newbcast:11 row_mask:0xf bank_mask:0xf
	v_fmac_f32_dpp v40, -v54, v12 row_newbcast:12 row_mask:0xf bank_mask:0xf
	v_fmac_f32_dpp v41, -v54, v13 row_newbcast:13 row_mask:0xf bank_mask:0xf
	v_fmac_f32_dpp v40, -v54, v14 row_newbcast:14 row_mask:0xf bank_mask:0xf
	v_fmac_f32_dpp v41, -v54, v15 row_newbcast:15 row_mask:0xf bank_mask:0xf
	v_fmac_f32_dpp v40, -v55, v16 row_newbcast:0 row_mask:0xf bank_mask:0xf
	v_fmac_f32_dpp v41, -v55, v17 row_newbcast:1 row_mask:0xf bank_mask:0xf
	v_fmac_f32_dpp v40, -v55, v18 row_newbcast:2 row_mask:0xf bank_mask:0xf
	v_fmac_f32_dpp v41, -v55, v19 row_newbcast:3 row_mask:0xf bank_mask:0xf
	v_fmac_f32_dpp v40, -v55, v20 row_newbcast:4 row_mask:0xf bank_mask:0xf
	v_fmac_f32_dpp v41, -v55, v21 row_newbcast:5 row_mask:0xf bank_mask:0xf
	v_fmac_f32_dpp v40, -v55, v22 row_newbcast:6 row_mask:0xf bank_mask:0xf
	v_fmac_f32_dpp v41, -v55, v23 row_newbcast:7 row_mask:0xf bank_mask:0xf
	ds_read_b32 v59, v38 offset:52224
	ds_read_b32 v54, v37 offset:13056
	ds_read_b32 v55, v37 offset:13184
	v_add_f32_e32 v42, v40, v41
	v_mov_b32_e32 v43, v42
	s_nop 1
	v_permlane32_swap_b32_e32 v42, v43
	s_nop 1
	v_add_f32_dpp v23, v42, v43 quad_perm:[0,1,2,3] row_mask:0xc bank_mask:0xf
	s_waitcnt lgkmcnt(9)
	v_mul_f32_e32 v40, v56, v39
	v_mov_b32_e32 v41, 0
	v_fmac_f32_dpp v40, -v48, v0 row_newbcast:0 row_mask:0xf bank_mask:0xf
	v_fmac_f32_dpp v41, -v48, v1 row_newbcast:1 row_mask:0xf bank_mask:0xf
	v_fmac_f32_dpp v40, -v48, v2 row_newbcast:2 row_mask:0xf bank_mask:0xf
	v_fmac_f32_dpp v41, -v48, v3 row_newbcast:3 row_mask:0xf bank_mask:0xf
	v_fmac_f32_dpp v40, -v48, v4 row_newbcast:4 row_mask:0xf bank_mask:0xf
	v_fmac_f32_dpp v41, -v48, v5 row_newbcast:5 row_mask:0xf bank_mask:0xf
	v_fmac_f32_dpp v40, -v48, v6 row_newbcast:6 row_mask:0xf bank_mask:0xf
	v_fmac_f32_dpp v41, -v48, v7 row_newbcast:7 row_mask:0xf bank_mask:0xf
	v_fmac_f32_dpp v40, -v48, v8 row_newbcast:8 row_mask:0xf bank_mask:0xf
	v_fmac_f32_dpp v41, -v48, v9 row_newbcast:9 row_mask:0xf bank_mask:0xf
	v_fmac_f32_dpp v40, -v48, v10 row_newbcast:10 row_mask:0xf bank_mask:0xf
	v_fmac_f32_dpp v41, -v48, v11 row_newbcast:11 row_mask:0xf bank_mask:0xf
	v_fmac_f32_dpp v40, -v48, v12 row_newbcast:12 row_mask:0xf bank_mask:0xf
	v_fmac_f32_dpp v41, -v48, v13 row_newbcast:13 row_mask:0xf bank_mask:0xf
	v_fmac_f32_dpp v40, -v48, v14 row_newbcast:14 row_mask:0xf bank_mask:0xf
	v_fmac_f32_dpp v41, -v48, v15 row_newbcast:15 row_mask:0xf bank_mask:0xf
	v_fmac_f32_dpp v40, -v49, v16 row_newbcast:0 row_mask:0xf bank_mask:0xf
	v_fmac_f32_dpp v41, -v49, v17 row_newbcast:1 row_mask:0xf bank_mask:0xf
	v_fmac_f32_dpp v40, -v49, v18 row_newbcast:2 row_mask:0xf bank_mask:0xf
	v_fmac_f32_dpp v41, -v49, v19 row_newbcast:3 row_mask:0xf bank_mask:0xf
	v_fmac_f32_dpp v40, -v49, v20 row_newbcast:4 row_mask:0xf bank_mask:0xf
	v_fmac_f32_dpp v41, -v49, v21 row_newbcast:5 row_mask:0xf bank_mask:0xf
	v_fmac_f32_dpp v40, -v49, v22 row_newbcast:6 row_mask:0xf bank_mask:0xf
	v_fmac_f32_dpp v41, -v49, v23 row_newbcast:7 row_mask:0xf bank_mask:0xf
	ds_read_b32 v56, v38 offset:53248
	ds_read_b32 v48, v37 offset:13312
	ds_read_b32 v49, v37 offset:13440
	v_add_f32_e32 v42, v40, v41
	v_mov_b32_e32 v43, v42
	s_nop 1
	v_permlane32_swap_b32_e32 v42, v43
	s_nop 1
	v_add_f32_dpp v24, v42, v43 quad_perm:[0,1,2,3] row_mask:0x3 bank_mask:0xf
	s_waitcnt lgkmcnt(9)
; #define LAS __attribute__((address_space(3)))
; __device__ __forceinline__ void phase_chunk_prep(const Params& p, LAS unsigned char* lds, int wave_s) {
;     ...
;             for (int i = 0; i < 64; ++i) {
;                 float s0 = RHS[i * 256 + col], s1 = 0.f, s2 = 0.f, s3 = 0.f;
; #pragma unroll
;                 for (int j4 = 0; j4 < (i + 3) / 4; ++j4) { const f32x4 a = *(const LAS f32x4*)(AM + i * 64 + 4 * j4);
;                     s0 -= a.x * sol[4 * j4]; s1 -= a.y * sol[4 * j4 + 1]; s2 -= a.z * sol[4 * j4 + 2]; s3 -= a.w * sol[4 * j4 + 3]; }
;                 sol[i] = (s0 + s1) + (s2 + s3);
;             }
	v_mul_f32_e32 v40, v57, v39
	v_mov_b32_e32 v41, 0
	v_fmac_f32_dpp v40, -v50, v0 row_newbcast:0 row_mask:0xf bank_mask:0xf
	v_fmac_f32_dpp v41, -v50, v1 row_newbcast:1 row_mask:0xf bank_mask:0xf
	v_fmac_f32_dpp v40, -v50, v2 row_newbcast:2 row_mask:0xf bank_mask:0xf
	v_fmac_f32_dpp v41, -v50, v3 row_newbcast:3 row_mask:0xf bank_mask:0xf
	v_fmac_f32_dpp v40, -v50, v4 row_newbcast:4 row_mask:0xf bank_mask:0xf
	v_fmac_f32_dpp v41, -v50, v5 row_newbcast:5 row_mask:0xf bank_mask:0xf
	v_fmac_f32_dpp v40, -v50, v6 row_newbcast:6 row_mask:0xf bank_mask:0xf
	v_fmac_f32_dpp v41, -v50, v7 row_newbcast:7 row_mask:0xf bank_mask:0xf
	v_fmac_f32_dpp v40, -v50, v8 row_newbcast:8 row_mask:0xf bank_mask:0xf
	v_fmac_f32_dpp v41, -v50, v9 row_newbcast:9 row_mask:0xf bank_mask:0xf
	v_fmac_f32_dpp v40, -v50, v10 row_newbcast:10 row_mask:0xf bank_mask:0xf
	v_fmac_f32_dpp v41, -v50, v11 row_newbcast:11 row_mask:0xf bank_mask:0xf
	v_fmac_f32_dpp v40, -v50, v12 row_newbcast:12 row_mask:0xf bank_mask:0xf
	v_fmac_f32_dpp v41, -v50, v13 row_newbcast:13 row_mask:0xf bank_mask:0xf
	v_fmac_f32_dpp v40, -v50, v14 row_newbcast:14 row_mask:0xf bank_mask:0xf
	v_fmac_f32_dpp v41, -v50, v15 row_newbcast:15 row_mask:0xf bank_mask:0xf
	v_fmac_f32_dpp v40, -v51, v16 row_newbcast:0 row_mask:0xf bank_mask:0xf
	v_fmac_f32_dpp v41, -v51, v17 row_newbcast:1 row_mask:0xf bank_mask:0xf
	v_fmac_f32_dpp v40, -v51, v18 row_newbcast:2 row_mask:0xf bank_mask:0xf
	v_fmac_f32_dpp v41, -v51, v19 row_newbcast:3 row_mask:0xf bank_mask:0xf
	v_fmac_f32_dpp v40, -v51, v20 row_newbcast:4 row_mask:0xf bank_mask:0xf
	v_fmac_f32_dpp v41, -v51, v21 row_newbcast:5 row_mask:0xf bank_mask:0xf
	v_fmac_f32_dpp v40, -v51, v22 row_newbcast:6 row_mask:0xf bank_mask:0xf
	v_fmac_f32_dpp v41, -v51, v23 row_newbcast:7 row_mask:0xf bank_mask:0xf
	v_fmac_f32_dpp v40, -v51, v24 row_newbcast:8 row_mask:0xf bank_mask:0xf
	ds_read_b32 v57, v38 offset:54272
	ds_read_b32 v50, v37 offset:13568
	ds_read_b32 v51, v37 offset:13696
	v_add_f32_e32 v42, v40, v41
	v_mov_b32_e32 v43, v42
	s_nop 1
	v_permlane32_swap_b32_e32 v42, v43
	s_nop 1
	v_add_f32_dpp v25, v42, v43 quad_perm:[0,1,2,3] row_mask:0x3 bank_mask:0xf
	s_waitcnt lgkmcnt(9)
	v_mul_f32_e32 v40, v58, v39
	v_mov_b32_e32 v41, 0
	v_fmac_f32_dpp v40, -v52, v0 row_newbcast:0 row_mask:0xf bank_mask:0xf
	v_fmac_f32_dpp v41, -v52, v1 row_newbcast:1 row_mask:0xf bank_mask:0xf
	v_fmac_f32_dpp v40, -v52, v2 row_newbcast:2 row_mask:0xf bank_mask:0xf
	v_fmac_f32_dpp v41, -v52, v3 row_newbcast:3 row_mask:0xf bank_mask:0xf
	v_fmac_f32_dpp v40, -v52, v4 row_newbcast:4 row_mask:0xf bank_mask:0xf
	v_fmac_f32_dpp v41, -v52, v5 row_newbcast:5 row_mask:0xf bank_mask:0xf
	v_fmac_f32_dpp v40, -v52, v6 row_newbcast:6 row_mask:0xf bank_mask:0xf
	v_fmac_f32_dpp v41, -v52, v7 row_newbcast:7 row_mask:0xf bank_mask:0xf
	v_fmac_f32_dpp v40, -v52, v8 row_newbcast:8 row_mask:0xf bank_mask:0xf
	v_fmac_f32_dpp v41, -v52, v9 row_newbcast:9 row_mask:0xf bank_mask:0xf
	v_fmac_f32_dpp v40, -v52, v10 row_newbcast:10 row_mask:0xf bank_mask:0xf
	v_fmac_f32_dpp v41, -v52, v11 row_newbcast:11 row_mask:0xf bank_mask:0xf
	v_fmac_f32_dpp v40, -v52, v12 row_newbcast:12 row_mask:0xf bank_mask:0xf
	v_fmac_f32_dpp v41, -v52, v13 row_newbcast:13 row_mask:0xf bank_mask:0xf
	v_fmac_f32_dpp v40, -v52, v14 row_newbcast:14 row_mask:0xf bank_mask:0xf
	v_fmac_f32_dpp v41, -v52, v15 row_newbcast:15 row_mask:0xf bank_mask:0xf
	v_fmac_f32_dpp v40, -v53, v16 row_newbcast:0 row_mask:0xf bank_mask:0xf
	v_fmac_f32_dpp v41, -v53, v17 row_newbcast:1 row_mask:0xf bank_mask:0xf
	v_fmac_f32_dpp v40, -v53, v18 row_newbcast:2 row_mask:0xf bank_mask:0xf
	v_fmac_f32_dpp v41, -v53, v19 row_newbcast:3 row_mask:0xf bank_mask:0xf
	v_fmac_f32_dpp v40, -v53, v20 row_newbcast:4 row_mask:0xf bank_mask:0xf
	v_fmac_f32_dpp v41, -v53, v21 row_newbcast:5 row_mask:0xf bank_mask:0xf
	v_fmac_f32_dpp v40, -v53, v22 row_newbcast:6 row_mask:0xf bank_mask:0xf
	v_fmac_f32_dpp v41, -v53, v23 row_newbcast:7 row_mask:0xf bank_mask:0xf
	v_fmac_f32_dpp v40, -v53, v24 row_newbcast:8 row_mask:0xf bank_mask:0xf
	v_fmac_f32_dpp v41, -v53, v25 row_newbcast:9 row_mask:0xf bank_mask:0xf
	ds_read_b32 v58, v38 offset:55296
	ds_read_b32 v52, v37 offset:13824
	ds_read_b32 v53, v37 offset:13952
	v_add_f32_e32 v42, v40, v41
	v_mov_b32_e32 v43, v42
	s_nop 1
	v_permlane32_swap_b32_e32 v42, v43
	s_nop 1
	v_add_f32_dpp v24, v42, v43 quad_perm:[0,1,2,3] row_mask:0xc bank_mask:0xf
	s_waitcnt lgkmcnt(9)
	v_mul_f32_e32 v40, v59, v39
	v_mov_b32_e32 v41, 0
	v_fmac_f32_dpp v40, -v54, v0 row_newbcast:0 row_mask:0xf bank_mask:0xf
	v_fmac_f32_dpp v41, -v54, v1 row_newbcast:1 row_mask:0xf bank_mask:0xf
	v_fmac_f32_dpp v40, -v54, v2 row_newbcast:2 row_mask:0xf bank_mask:0xf
	v_fmac_f32_dpp v41, -v54, v3 row_newbcast:3 row_mask:0xf bank_mask:0xf
	v_fmac_f32_dpp v40, -v54, v4 row_newbcast:4 row_mask:0xf bank_mask:0xf
	v_fmac_f32_dpp v41, -v54, v5 row_newbcast:5 row_mask:0xf bank_mask:0xf
	v_fmac_f32_dpp v40, -v54, v6 row_newbcast:6 row_mask:0xf bank_mask:0xf
	v_fmac_f32_dpp v41, -v54, v7 row_newbcast:7 row_mask:0xf bank_mask:0xf
	v_fmac_f32_dpp v40, -v54, v8 row_newbcast:8 row_mask:0xf bank_mask:0xf
	v_fmac_f32_dpp v41, -v54, v9 row_newbcast:9 row_mask:0xf bank_mask:0xf
	v_fmac_f32_dpp v40, -v54, v10 row_newbcast:10 row_mask:0xf bank_mask:0xf
	v_fmac_f32_dpp v41, -v54, v11 row_newbcast:11 row_mask:0xf bank_mask:0xf
	v_fmac_f32_dpp v40, -v54, v12 row_newbcast:12 row_mask:0xf bank_mask:0xf
	v_fmac_f32_dpp v41, -v54, v13 row_newbcast:13 row_mask:0xf bank_mask:0xf
	v_fmac_f32_dpp v40, -v54, v14 row_newbcast:14 row_mask:0xf bank_mask:0xf
	v_fmac_f32_dpp v41, -v54, v15 row_newbcast:15 row_mask:0xf bank_mask:0xf
	v_fmac_f32_dpp v40, -v55, v16 row_newbcast:0 row_mask:0xf bank_mask:0xf
	v_fmac_f32_dpp v41, -v55, v17 row_newbcast:1 row_mask:0xf bank_mask:0xf
	v_fmac_f32_dpp v40, -v55, v18 row_newbcast:2 row_mask:0xf bank_mask:0xf
	v_fmac_f32_dpp v41, -v55, v19 row_newbcast:3 row_mask:0xf bank_mask:0xf
	v_fmac_f32_dpp v40, -v55, v20 row_newbcast:4 row_mask:0xf bank_mask:0xf
	v_fmac_f32_dpp v41, -v55, v21 row_newbcast:5 row_mask:0xf bank_mask:0xf
	v_fmac_f32_dpp v40, -v55, v22 row_newbcast:6 row_mask:0xf bank_mask:0xf
	v_fmac_f32_dpp v41, -v55, v23 row_newbcast:7 row_mask:0xf bank_mask:0xf
	v_fmac_f32_dpp v40, -v55, v24 row_newbcast:8 row_mask:0xf bank_mask:0xf
	v_fmac_f32_dpp v41, -v55, v25 row_newbcast:9 row_mask:0xf bank_mask:0xf
	ds_read_b32 v59, v38 offset:56320
	ds_read_b32 v54, v37 offset:14080
	ds_read_b32 v55, v37 offset:14208
	v_add_f32_e32 v42, v40, v41
	v_mov_b32_e32 v43, v42
	s_nop 1
	v_permlane32_swap_b32_e32 v42, v43
	s_nop 1
	v_add_f32_dpp v25, v42, v43 quad_perm:[0,1,2,3] row_mask:0xc bank_mask:0xf
	s_waitcnt lgkmcnt(9)
; #define LAS __attribute__((address_space(3)))
; __device__ __forceinline__ void phase_chunk_prep(const Params& p, LAS unsigned char* lds, int wave_s) {
;     ...
;             for (int i = 0; i < 64; ++i) {
;                 float s0 = RHS[i * 256 + col], s1 = 0.f, s2 = 0.f, s3 = 0.f;
; #pragma unroll
;                 for (int j4 = 0; j4 < (i + 3) / 4; ++j4) { const f32x4 a = *(const LAS f32x4*)(AM + i * 64 + 4 * j4);
;                     s0 -= a.x * sol[4 * j4]; s1 -= a.y * sol[4 * j4 + 1]; s2 -= a.z * sol[4 * j4 + 2]; s3 -= a.w * sol[4 * j4 + 3]; }
;                 sol[i] = (s0 + s1) + (s2 + s3);
;             }
	v_mul_f32_e32 v40, v56, v39
	v_mov_b32_e32 v41, 0
	v_fmac_f32_dpp v40, -v48, v0 row_newbcast:0 row_mask:0xf bank_mask:0xf
	v_fmac_f32_dpp v41, -v48, v1 row_newbcast:1 row_mask:0xf bank_mask:0xf
	v_fmac_f32_dpp v40, -v48, v2 row_newbcast:2 row_mask:0xf bank_mask:0xf
	v_fmac_f32_dpp v41, -v48, v3 row_newbcast:3 row_mask:0xf bank_mask:0xf
	v_fmac_f32_dpp v40, -v48, v4 row_newbcast:4 row_mask:0xf bank_mask:0xf
	v_fmac_f32_dpp v41, -v48, v5 row_newbcast:5 row_mask:0xf bank_mask:0xf
	v_fmac_f32_dpp v40, -v48, v6 row_newbcast:6 row_mask:0xf bank_mask:0xf
	v_fmac_f32_dpp v41, -v48, v7 row_newbcast:7 row_mask:0xf bank_mask:0xf
	v_fmac_f32_dpp v40, -v48, v8 row_newbcast:8 row_mask:0xf bank_mask:0xf
	v_fmac_f32_dpp v41, -v48, v9 row_newbcast:9 row_mask:0xf bank_mask:0xf
	v_fmac_f32_dpp v40, -v48, v10 row_newbcast:10 row_mask:0xf bank_mask:0xf
	v_fmac_f32_dpp v41, -v48, v11 row_newbcast:11 row_mask:0xf bank_mask:0xf
	v_fmac_f32_dpp v40, -v48, v12 row_newbcast:12 row_mask:0xf bank_mask:0xf
	v_fmac_f32_dpp v41, -v48, v13 row_newbcast:13 row_mask:0xf bank_mask:0xf
	v_fmac_f32_dpp v40, -v48, v14 row_newbcast:14 row_mask:0xf bank_mask:0xf
	v_fmac_f32_dpp v41, -v48, v15 row_newbcast:15 row_mask:0xf bank_mask:0xf
	v_fmac_f32_dpp v40, -v49, v16 row_newbcast:0 row_mask:0xf bank_mask:0xf
	v_fmac_f32_dpp v41, -v49, v17 row_newbcast:1 row_mask:0xf bank_mask:0xf
	v_fmac_f32_dpp v40, -v49, v18 row_newbcast:2 row_mask:0xf bank_mask:0xf
	v_fmac_f32_dpp v41, -v49, v19 row_newbcast:3 row_mask:0xf bank_mask:0xf
	v_fmac_f32_dpp v40, -v49, v20 row_newbcast:4 row_mask:0xf bank_mask:0xf
	v_fmac_f32_dpp v41, -v49, v21 row_newbcast:5 row_mask:0xf bank_mask:0xf
	v_fmac_f32_dpp v40, -v49, v22 row_newbcast:6 row_mask:0xf bank_mask:0xf
	v_fmac_f32_dpp v41, -v49, v23 row_newbcast:7 row_mask:0xf bank_mask:0xf
	v_fmac_f32_dpp v40, -v49, v24 row_newbcast:8 row_mask:0xf bank_mask:0xf
	v_fmac_f32_dpp v41, -v49, v25 row_newbcast:9 row_mask:0xf bank_mask:0xf
	ds_read_b32 v56, v38 offset:57344
	ds_read_b32 v48, v37 offset:14336
	ds_read_b32 v49, v37 offset:14464
	v_add_f32_e32 v42, v40, v41
	v_mov_b32_e32 v43, v42
	s_nop 1
	v_permlane32_swap_b32_e32 v42, v43
	s_nop 1
	v_add_f32_dpp v26, v42, v43 quad_perm:[0,1,2,3] row_mask:0x3 bank_mask:0xf
	s_waitcnt lgkmcnt(9)
	v_mul_f32_e32 v40, v57, v39
	v_mov_b32_e32 v41, 0
	v_fmac_f32_dpp v40, -v50, v0 row_newbcast:0 row_mask:0xf bank_mask:0xf
	v_fmac_f32_dpp v41, -v50, v1 row_newbcast:1 row_mask:0xf bank_mask:0xf
	v_fmac_f32_dpp v40, -v50, v2 row_newbcast:2 row_mask:0xf bank_mask:0xf
	v_fmac_f32_dpp v41, -v50, v3 row_newbcast:3 row_mask:0xf bank_mask:0xf
	v_fmac_f32_dpp v40, -v50, v4 row_newbcast:4 row_mask:0xf bank_mask:0xf
	v_fmac_f32_dpp v41, -v50, v5 row_newbcast:5 row_mask:0xf bank_mask:0xf
	v_fmac_f32_dpp v40, -v50, v6 row_newbcast:6 row_mask:0xf bank_mask:0xf
	v_fmac_f32_dpp v41, -v50, v7 row_newbcast:7 row_mask:0xf bank_mask:0xf
	v_fmac_f32_dpp v40, -v50, v8 row_newbcast:8 row_mask:0xf bank_mask:0xf
	v_fmac_f32_dpp v41, -v50, v9 row_newbcast:9 row_mask:0xf bank_mask:0xf
	v_fmac_f32_dpp v40, -v50, v10 row_newbcast:10 row_mask:0xf bank_mask:0xf
	v_fmac_f32_dpp v41, -v50, v11 row_newbcast:11 row_mask:0xf bank_mask:0xf
	v_fmac_f32_dpp v40, -v50, v12 row_newbcast:12 row_mask:0xf bank_mask:0xf
	v_fmac_f32_dpp v41, -v50, v13 row_newbcast:13 row_mask:0xf bank_mask:0xf
	v_fmac_f32_dpp v40, -v50, v14 row_newbcast:14 row_mask:0xf bank_mask:0xf
	v_fmac_f32_dpp v41, -v50, v15 row_newbcast:15 row_mask:0xf bank_mask:0xf
	v_fmac_f32_dpp v40, -v51, v16 row_newbcast:0 row_mask:0xf bank_mask:0xf
	v_fmac_f32_dpp v41, -v51, v17 row_newbcast:1 row_mask:0xf bank_mask:0xf
	v_fmac_f32_dpp v40, -v51, v18 row_newbcast:2 row_mask:0xf bank_mask:0xf
	v_fmac_f32_dpp v41, -v51, v19 row_newbcast:3 row_mask:0xf bank_mask:0xf
	v_fmac_f32_dpp v40, -v51, v20 row_newbcast:4 row_mask:0xf bank_mask:0xf
	v_fmac_f32_dpp v41, -v51, v21 row_newbcast:5 row_mask:0xf bank_mask:0xf
	v_fmac_f32_dpp v40, -v51, v22 row_newbcast:6 row_mask:0xf bank_mask:0xf
	v_fmac_f32_dpp v41, -v51, v23 row_newbcast:7 row_mask:0xf bank_mask:0xf
	v_fmac_f32_dpp v40, -v51, v24 row_newbcast:8 row_mask:0xf bank_mask:0xf
	v_fmac_f32_dpp v41, -v51, v25 row_newbcast:9 row_mask:0xf bank_mask:0xf
	v_fmac_f32_dpp v40, -v51, v26 row_newbcast:10 row_mask:0xf bank_mask:0xf
	ds_read_b32 v57, v38 offset:58368
	ds_read_b32 v50, v37 offset:14592
	ds_read_b32 v51, v37 offset:14720
	v_add_f32_e32 v42, v40, v41
	v_mov_b32_e32 v43, v42
	s_nop 1
	v_permlane32_swap_b32_e32 v42, v43
	s_nop 1
	v_add_f32_dpp v27, v42, v43 quad_perm:[0,1,2,3] row_mask:0x3 bank_mask:0xf
	s_waitcnt lgkmcnt(9)
; #define LAS __attribute__((address_space(3)))
; __device__ __forceinline__ void phase_chunk_prep(const Params& p, LAS unsigned char* lds, int wave_s) {
;     ...
;             for (int i = 0; i < 64; ++i) {
;                 float s0 = RHS[i * 256 + col], s1 = 0.f, s2 = 0.f, s3 = 0.f;
; #pragma unroll
;                 for (int j4 = 0; j4 < (i + 3) / 4; ++j4) { const f32x4 a = *(const LAS f32x4*)(AM + i * 64 + 4 * j4);
;                     s0 -= a.x * sol[4 * j4]; s1 -= a.y * sol[4 * j4 + 1]; s2 -= a.z * sol[4 * j4 + 2]; s3 -= a.w * sol[4 * j4 + 3]; }
;                 sol[i] = (s0 + s1) + (s2 + s3);
;             }
	v_mul_f32_e32 v40, v58, v39
	v_mov_b32_e32 v41, 0
	v_fmac_f32_dpp v40, -v52, v0 row_newbcast:0 row_mask:0xf bank_mask:0xf
	v_fmac_f32_dpp v41, -v52, v1 row_newbcast:1 row_mask:0xf bank_mask:0xf
	v_fmac_f32_dpp v40, -v52, v2 row_newbcast:2 row_mask:0xf bank_mask:0xf
	v_fmac_f32_dpp v41, -v52, v3 row_newbcast:3 row_mask:0xf bank_mask:0xf
	v_fmac_f32_dpp v40, -v52, v4 row_newbcast:4 row_mask:0xf bank_mask:0xf
	v_fmac_f32_dpp v41, -v52, v5 row_newbcast:5 row_mask:0xf bank_mask:0xf
	v_fmac_f32_dpp v40, -v52, v6 row_newbcast:6 row_mask:0xf bank_mask:0xf
	v_fmac_f32_dpp v41, -v52, v7 row_newbcast:7 row_mask:0xf bank_mask:0xf
	v_fmac_f32_dpp v40, -v52, v8 row_newbcast:8 row_mask:0xf bank_mask:0xf
	v_fmac_f32_dpp v41, -v52, v9 row_newbcast:9 row_mask:0xf bank_mask:0xf
	v_fmac_f32_dpp v40, -v52, v10 row_newbcast:10 row_mask:0xf bank_mask:0xf
	v_fmac_f32_dpp v41, -v52, v11 row_newbcast:11 row_mask:0xf bank_mask:0xf
	v_fmac_f32_dpp v40, -v52, v12 row_newbcast:12 row_mask:0xf bank_mask:0xf
	v_fmac_f32_dpp v41, -v52, v13 row_newbcast:13 row_mask:0xf bank_mask:0xf
	v_fmac_f32_dpp v40, -v52, v14 row_newbcast:14 row_mask:0xf bank_mask:0xf
	v_fmac_f32_dpp v41, -v52, v15 row_newbcast:15 row_mask:0xf bank_mask:0xf
	v_fmac_f32_dpp v40, -v53, v16 row_newbcast:0 row_mask:0xf bank_mask:0xf
	v_fmac_f32_dpp v41, -v53, v17 row_newbcast:1 row_mask:0xf bank_mask:0xf
	v_fmac_f32_dpp v40, -v53, v18 row_newbcast:2 row_mask:0xf bank_mask:0xf
	v_fmac_f32_dpp v41, -v53, v19 row_newbcast:3 row_mask:0xf bank_mask:0xf
	v_fmac_f32_dpp v40, -v53, v20 row_newbcast:4 row_mask:0xf bank_mask:0xf
	v_fmac_f32_dpp v41, -v53, v21 row_newbcast:5 row_mask:0xf bank_mask:0xf
	v_fmac_f32_dpp v40, -v53, v22 row_newbcast:6 row_mask:0xf bank_mask:0xf
	v_fmac_f32_dpp v41, -v53, v23 row_newbcast:7 row_mask:0xf bank_mask:0xf
	v_fmac_f32_dpp v40, -v53, v24 row_newbcast:8 row_mask:0xf bank_mask:0xf
	v_fmac_f32_dpp v41, -v53, v25 row_newbcast:9 row_mask:0xf bank_mask:0xf
	v_fmac_f32_dpp v40, -v53, v26 row_newbcast:10 row_mask:0xf bank_mask:0xf
	v_fmac_f32_dpp v41, -v53, v27 row_newbcast:11 row_mask:0xf bank_mask:0xf
	ds_read_b32 v58, v38 offset:59392
	ds_read_b32 v52, v37 offset:14848
	ds_read_b32 v53, v37 offset:14976
	v_add_f32_e32 v42, v40, v41
	v_mov_b32_e32 v43, v42
	s_nop 1
	v_permlane32_swap_b32_e32 v42, v43
	s_nop 1
	v_add_f32_dpp v26, v42, v43 quad_perm:[0,1,2,3] row_mask:0xc bank_mask:0xf
	s_waitcnt lgkmcnt(9)
	v_mul_f32_e32 v40, v59, v39
	v_mov_b32_e32 v41, 0
	v_fmac_f32_dpp v40, -v54, v0 row_newbcast:0 row_mask:0xf bank_mask:0xf
	v_fmac_f32_dpp v41, -v54, v1 row_newbcast:1 row_mask:0xf bank_mask:0xf
	v_fmac_f32_dpp v40, -v54, v2 row_newbcast:2 row_mask:0xf bank_mask:0xf
	v_fmac_f32_dpp v41, -v54, v3 row_newbcast:3 row_mask:0xf bank_mask:0xf
	v_fmac_f32_dpp v40, -v54, v4 row_newbcast:4 row_mask:0xf bank_mask:0xf
	v_fmac_f32_dpp v41, -v54, v5 row_newbcast:5 row_mask:0xf bank_mask:0xf
	v_fmac_f32_dpp v40, -v54, v6 row_newbcast:6 row_mask:0xf bank_mask:0xf
	v_fmac_f32_dpp v41, -v54, v7 row_newbcast:7 row_mask:0xf bank_mask:0xf
	v_fmac_f32_dpp v40, -v54, v8 row_newbcast:8 row_mask:0xf bank_mask:0xf
	v_fmac_f32_dpp v41, -v54, v9 row_newbcast:9 row_mask:0xf bank_mask:0xf
	v_fmac_f32_dpp v40, -v54, v10 row_newbcast:10 row_mask:0xf bank_mask:0xf
	v_fmac_f32_dpp v41, -v54, v11 row_newbcast:11 row_mask:0xf bank_mask:0xf
	v_fmac_f32_dpp v40, -v54, v12 row_newbcast:12 row_mask:0xf bank_mask:0xf
	v_fmac_f32_dpp v41, -v54, v13 row_newbcast:13 row_mask:0xf bank_mask:0xf
	v_fmac_f32_dpp v40, -v54, v14 row_newbcast:14 row_mask:0xf bank_mask:0xf
	v_fmac_f32_dpp v41, -v54, v15 row_newbcast:15 row_mask:0xf bank_mask:0xf
	v_fmac_f32_dpp v40, -v55, v16 row_newbcast:0 row_mask:0xf bank_mask:0xf
	v_fmac_f32_dpp v41, -v55, v17 row_newbcast:1 row_mask:0xf bank_mask:0xf
	v_fmac_f32_dpp v40, -v55, v18 row_newbcast:2 row_mask:0xf bank_mask:0xf
	v_fmac_f32_dpp v41, -v55, v19 row_newbcast:3 row_mask:0xf bank_mask:0xf
	v_fmac_f32_dpp v40, -v55, v20 row_newbcast:4 row_mask:0xf bank_mask:0xf
	v_fmac_f32_dpp v41, -v55, v21 row_newbcast:5 row_mask:0xf bank_mask:0xf
	v_fmac_f32_dpp v40, -v55, v22 row_newbcast:6 row_mask:0xf bank_mask:0xf
	v_fmac_f32_dpp v41, -v55, v23 row_newbcast:7 row_mask:0xf bank_mask:0xf
	v_fmac_f32_dpp v40, -v55, v24 row_newbcast:8 row_mask:0xf bank_mask:0xf
	v_fmac_f32_dpp v41, -v55, v25 row_newbcast:9 row_mask:0xf bank_mask:0xf
	v_fmac_f32_dpp v40, -v55, v26 row_newbcast:10 row_mask:0xf bank_mask:0xf
	v_fmac_f32_dpp v41, -v55, v27 row_newbcast:11 row_mask:0xf bank_mask:0xf
	ds_read_b32 v59, v38 offset:60416
	ds_read_b32 v54, v37 offset:15104
	ds_read_b32 v55, v37 offset:15232
	v_add_f32_e32 v42, v40, v41
	v_mov_b32_e32 v43, v42
	s_nop 1
	v_permlane32_swap_b32_e32 v42, v43
	s_nop 1
	v_add_f32_dpp v27, v42, v43 quad_perm:[0,1,2,3] row_mask:0xc bank_mask:0xf
	s_waitcnt lgkmcnt(9)
; #define LAS __attribute__((address_space(3)))
; __device__ __forceinline__ void phase_chunk_prep(const Params& p, LAS unsigned char* lds, int wave_s) {
;     ...
;             for (int i = 0; i < 64; ++i) {
;                 float s0 = RHS[i * 256 + col], s1 = 0.f, s2 = 0.f, s3 = 0.f;
; #pragma unroll
;                 for (int j4 = 0; j4 < (i + 3) / 4; ++j4) { const f32x4 a = *(const LAS f32x4*)(AM + i * 64 + 4 * j4);
;                     s0 -= a.x * sol[4 * j4]; s1 -= a.y * sol[4 * j4 + 1]; s2 -= a.z * sol[4 * j4 + 2]; s3 -= a.w * sol[4 * j4 + 3]; }
;                 sol[i] = (s0 + s1) + (s2 + s3);
;             }
	v_mul_f32_e32 v40, v56, v39
	v_mov_b32_e32 v41, 0
	v_fmac_f32_dpp v40, -v48, v0 row_newbcast:0 row_mask:0xf bank_mask:0xf
	v_fmac_f32_dpp v41, -v48, v1 row_newbcast:1 row_mask:0xf bank_mask:0xf
	v_fmac_f32_dpp v40, -v48, v2 row_newbcast:2 row_mask:0xf bank_mask:0xf
	v_fmac_f32_dpp v41, -v48, v3 row_newbcast:3 row_mask:0xf bank_mask:0xf
	v_fmac_f32_dpp v40, -v48, v4 row_newbcast:4 row_mask:0xf bank_mask:0xf
	v_fmac_f32_dpp v41, -v48, v5 row_newbcast:5 row_mask:0xf bank_mask:0xf
	v_fmac_f32_dpp v40, -v48, v6 row_newbcast:6 row_mask:0xf bank_mask:0xf
	v_fmac_f32_dpp v41, -v48, v7 row_newbcast:7 row_mask:0xf bank_mask:0xf
	v_fmac_f32_dpp v40, -v48, v8 row_newbcast:8 row_mask:0xf bank_mask:0xf
	v_fmac_f32_dpp v41, -v48, v9 row_newbcast:9 row_mask:0xf bank_mask:0xf
	v_fmac_f32_dpp v40, -v48, v10 row_newbcast:10 row_mask:0xf bank_mask:0xf
	v_fmac_f32_dpp v41, -v48, v11 row_newbcast:11 row_mask:0xf bank_mask:0xf
	v_fmac_f32_dpp v40, -v48, v12 row_newbcast:12 row_mask:0xf bank_mask:0xf
	v_fmac_f32_dpp v41, -v48, v13 row_newbcast:13 row_mask:0xf bank_mask:0xf
	v_fmac_f32_dpp v40, -v48, v14 row_newbcast:14 row_mask:0xf bank_mask:0xf
	v_fmac_f32_dpp v41, -v48, v15 row_newbcast:15 row_mask:0xf bank_mask:0xf
	v_fmac_f32_dpp v40, -v49, v16 row_newbcast:0 row_mask:0xf bank_mask:0xf
	v_fmac_f32_dpp v41, -v49, v17 row_newbcast:1 row_mask:0xf bank_mask:0xf
	v_fmac_f32_dpp v40, -v49, v18 row_newbcast:2 row_mask:0xf bank_mask:0xf
	v_fmac_f32_dpp v41, -v49, v19 row_newbcast:3 row_mask:0xf bank_mask:0xf
	v_fmac_f32_dpp v40, -v49, v20 row_newbcast:4 row_mask:0xf bank_mask:0xf
	v_fmac_f32_dpp v41, -v49, v21 row_newbcast:5 row_mask:0xf bank_mask:0xf
	v_fmac_f32_dpp v40, -v49, v22 row_newbcast:6 row_mask:0xf bank_mask:0xf
	v_fmac_f32_dpp v41, -v49, v23 row_newbcast:7 row_mask:0xf bank_mask:0xf
	v_fmac_f32_dpp v40, -v49, v24 row_newbcast:8 row_mask:0xf bank_mask:0xf
	v_fmac_f32_dpp v41, -v49, v25 row_newbcast:9 row_mask:0xf bank_mask:0xf
	v_fmac_f32_dpp v40, -v49, v26 row_newbcast:10 row_mask:0xf bank_mask:0xf
	v_fmac_f32_dpp v41, -v49, v27 row_newbcast:11 row_mask:0xf bank_mask:0xf
	ds_read_b32 v56, v38 offset:61440
	ds_read_b32 v48, v37 offset:15360
	ds_read_b32 v49, v37 offset:15488
	v_add_f32_e32 v42, v40, v41
	v_mov_b32_e32 v43, v42
	s_nop 1
	v_permlane32_swap_b32_e32 v42, v43
	s_nop 1
	v_add_f32_dpp v28, v42, v43 quad_perm:[0,1,2,3] row_mask:0x3 bank_mask:0xf
	s_waitcnt lgkmcnt(9)
	v_mul_f32_e32 v40, v57, v39
	v_mov_b32_e32 v41, 0
	v_fmac_f32_dpp v40, -v50, v0 row_newbcast:0 row_mask:0xf bank_mask:0xf
	v_fmac_f32_dpp v41, -v50, v1 row_newbcast:1 row_mask:0xf bank_mask:0xf
	v_fmac_f32_dpp v40, -v50, v2 row_newbcast:2 row_mask:0xf bank_mask:0xf
	v_fmac_f32_dpp v41, -v50, v3 row_newbcast:3 row_mask:0xf bank_mask:0xf
	v_fmac_f32_dpp v40, -v50, v4 row_newbcast:4 row_mask:0xf bank_mask:0xf
	v_fmac_f32_dpp v41, -v50, v5 row_newbcast:5 row_mask:0xf bank_mask:0xf
	v_fmac_f32_dpp v40, -v50, v6 row_newbcast:6 row_mask:0xf bank_mask:0xf
	v_fmac_f32_dpp v41, -v50, v7 row_newbcast:7 row_mask:0xf bank_mask:0xf
	v_fmac_f32_dpp v40, -v50, v8 row_newbcast:8 row_mask:0xf bank_mask:0xf
	v_fmac_f32_dpp v41, -v50, v9 row_newbcast:9 row_mask:0xf bank_mask:0xf
	v_fmac_f32_dpp v40, -v50, v10 row_newbcast:10 row_mask:0xf bank_mask:0xf
	v_fmac_f32_dpp v41, -v50, v11 row_newbcast:11 row_mask:0xf bank_mask:0xf
	v_fmac_f32_dpp v40, -v50, v12 row_newbcast:12 row_mask:0xf bank_mask:0xf
	v_fmac_f32_dpp v41, -v50, v13 row_newbcast:13 row_mask:0xf bank_mask:0xf
	v_fmac_f32_dpp v40, -v50, v14 row_newbcast:14 row_mask:0xf bank_mask:0xf
	v_fmac_f32_dpp v41, -v50, v15 row_newbcast:15 row_mask:0xf bank_mask:0xf
	v_fmac_f32_dpp v40, -v51, v16 row_newbcast:0 row_mask:0xf bank_mask:0xf
	v_fmac_f32_dpp v41, -v51, v17 row_newbcast:1 row_mask:0xf bank_mask:0xf
	v_fmac_f32_dpp v40, -v51, v18 row_newbcast:2 row_mask:0xf bank_mask:0xf
	v_fmac_f32_dpp v41, -v51, v19 row_newbcast:3 row_mask:0xf bank_mask:0xf
	v_fmac_f32_dpp v40, -v51, v20 row_newbcast:4 row_mask:0xf bank_mask:0xf
	v_fmac_f32_dpp v41, -v51, v21 row_newbcast:5 row_mask:0xf bank_mask:0xf
	v_fmac_f32_dpp v40, -v51, v22 row_newbcast:6 row_mask:0xf bank_mask:0xf
	v_fmac_f32_dpp v41, -v51, v23 row_newbcast:7 row_mask:0xf bank_mask:0xf
	v_fmac_f32_dpp v40, -v51, v24 row_newbcast:8 row_mask:0xf bank_mask:0xf
	v_fmac_f32_dpp v41, -v51, v25 row_newbcast:9 row_mask:0xf bank_mask:0xf
	v_fmac_f32_dpp v40, -v51, v26 row_newbcast:10 row_mask:0xf bank_mask:0xf
	v_fmac_f32_dpp v41, -v51, v27 row_newbcast:11 row_mask:0xf bank_mask:0xf
	v_fmac_f32_dpp v40, -v51, v28 row_newbcast:12 row_mask:0xf bank_mask:0xf
	ds_read_b32 v57, v38 offset:62464
	ds_read_b32 v50, v37 offset:15616
	ds_read_b32 v51, v37 offset:15744
	v_add_f32_e32 v42, v40, v41
	v_mov_b32_e32 v43, v42
	s_nop 1
	v_permlane32_swap_b32_e32 v42, v43
	s_nop 1
	v_add_f32_dpp v29, v42, v43 quad_perm:[0,1,2,3] row_mask:0x3 bank_mask:0xf
	s_waitcnt lgkmcnt(9)
; #define LAS __attribute__((address_space(3)))
; __device__ __forceinline__ void phase_chunk_prep(const Params& p, LAS unsigned char* lds, int wave_s) {
;     ...
;             for (int i = 0; i < 64; ++i) {
;                 float s0 = RHS[i * 256 + col], s1 = 0.f, s2 = 0.f, s3 = 0.f;
; #pragma unroll
;                 for (int j4 = 0; j4 < (i + 3) / 4; ++j4) { const f32x4 a = *(const LAS f32x4*)(AM + i * 64 + 4 * j4);
;                     s0 -= a.x * sol[4 * j4]; s1 -= a.y * sol[4 * j4 + 1]; s2 -= a.z * sol[4 * j4 + 2]; s3 -= a.w * sol[4 * j4 + 3]; }
;                 sol[i] = (s0 + s1) + (s2 + s3);
;             }
	v_mul_f32_e32 v40, v58, v39
	v_mov_b32_e32 v41, 0
	v_fmac_f32_dpp v40, -v52, v0 row_newbcast:0 row_mask:0xf bank_mask:0xf
	v_fmac_f32_dpp v41, -v52, v1 row_newbcast:1 row_mask:0xf bank_mask:0xf
	v_fmac_f32_dpp v40, -v52, v2 row_newbcast:2 row_mask:0xf bank_mask:0xf
	v_fmac_f32_dpp v41, -v52, v3 row_newbcast:3 row_mask:0xf bank_mask:0xf
	v_fmac_f32_dpp v40, -v52, v4 row_newbcast:4 row_mask:0xf bank_mask:0xf
	v_fmac_f32_dpp v41, -v52, v5 row_newbcast:5 row_mask:0xf bank_mask:0xf
	v_fmac_f32_dpp v40, -v52, v6 row_newbcast:6 row_mask:0xf bank_mask:0xf
	v_fmac_f32_dpp v41, -v52, v7 row_newbcast:7 row_mask:0xf bank_mask:0xf
	v_fmac_f32_dpp v40, -v52, v8 row_newbcast:8 row_mask:0xf bank_mask:0xf
	v_fmac_f32_dpp v41, -v52, v9 row_newbcast:9 row_mask:0xf bank_mask:0xf
	v_fmac_f32_dpp v40, -v52, v10 row_newbcast:10 row_mask:0xf bank_mask:0xf
	v_fmac_f32_dpp v41, -v52, v11 row_newbcast:11 row_mask:0xf bank_mask:0xf
	v_fmac_f32_dpp v40, -v52, v12 row_newbcast:12 row_mask:0xf bank_mask:0xf
	v_fmac_f32_dpp v41, -v52, v13 row_newbcast:13 row_mask:0xf bank_mask:0xf
	v_fmac_f32_dpp v40, -v52, v14 row_newbcast:14 row_mask:0xf bank_mask:0xf
	v_fmac_f32_dpp v41, -v52, v15 row_newbcast:15 row_mask:0xf bank_mask:0xf
	v_fmac_f32_dpp v40, -v53, v16 row_newbcast:0 row_mask:0xf bank_mask:0xf
	v_fmac_f32_dpp v41, -v53, v17 row_newbcast:1 row_mask:0xf bank_mask:0xf
	v_fmac_f32_dpp v40, -v53, v18 row_newbcast:2 row_mask:0xf bank_mask:0xf
	v_fmac_f32_dpp v41, -v53, v19 row_newbcast:3 row_mask:0xf bank_mask:0xf
	v_fmac_f32_dpp v40, -v53, v20 row_newbcast:4 row_mask:0xf bank_mask:0xf
	v_fmac_f32_dpp v41, -v53, v21 row_newbcast:5 row_mask:0xf bank_mask:0xf
	v_fmac_f32_dpp v40, -v53, v22 row_newbcast:6 row_mask:0xf bank_mask:0xf
	v_fmac_f32_dpp v41, -v53, v23 row_newbcast:7 row_mask:0xf bank_mask:0xf
	v_fmac_f32_dpp v40, -v53, v24 row_newbcast:8 row_mask:0xf bank_mask:0xf
	v_fmac_f32_dpp v41, -v53, v25 row_newbcast:9 row_mask:0xf bank_mask:0xf
	v_fmac_f32_dpp v40, -v53, v26 row_newbcast:10 row_mask:0xf bank_mask:0xf
	v_fmac_f32_dpp v41, -v53, v27 row_newbcast:11 row_mask:0xf bank_mask:0xf
	v_fmac_f32_dpp v40, -v53, v28 row_newbcast:12 row_mask:0xf bank_mask:0xf
	v_fmac_f32_dpp v41, -v53, v29 row_newbcast:13 row_mask:0xf bank_mask:0xf
	ds_read_b32 v58, v38 offset:63488
	ds_read_b32 v52, v37 offset:15872
	ds_read_b32 v53, v37 offset:16000
	v_add_f32_e32 v42, v40, v41
	v_mov_b32_e32 v43, v42
	s_nop 1
	v_permlane32_swap_b32_e32 v42, v43
	s_nop 1
	v_add_f32_dpp v28, v42, v43 quad_perm:[0,1,2,3] row_mask:0xc bank_mask:0xf
	s_waitcnt lgkmcnt(9)
	v_mul_f32_e32 v40, v59, v39
	v_mov_b32_e32 v41, 0
	v_fmac_f32_dpp v40, -v54, v0 row_newbcast:0 row_mask:0xf bank_mask:0xf
	v_fmac_f32_dpp v41, -v54, v1 row_newbcast:1 row_mask:0xf bank_mask:0xf
	v_fmac_f32_dpp v40, -v54, v2 row_newbcast:2 row_mask:0xf bank_mask:0xf
	v_fmac_f32_dpp v41, -v54, v3 row_newbcast:3 row_mask:0xf bank_mask:0xf
	v_fmac_f32_dpp v40, -v54, v4 row_newbcast:4 row_mask:0xf bank_mask:0xf
	v_fmac_f32_dpp v41, -v54, v5 row_newbcast:5 row_mask:0xf bank_mask:0xf
	v_fmac_f32_dpp v40, -v54, v6 row_newbcast:6 row_mask:0xf bank_mask:0xf
	v_fmac_f32_dpp v41, -v54, v7 row_newbcast:7 row_mask:0xf bank_mask:0xf
	v_fmac_f32_dpp v40, -v54, v8 row_newbcast:8 row_mask:0xf bank_mask:0xf
	v_fmac_f32_dpp v41, -v54, v9 row_newbcast:9 row_mask:0xf bank_mask:0xf
	v_fmac_f32_dpp v40, -v54, v10 row_newbcast:10 row_mask:0xf bank_mask:0xf
	v_fmac_f32_dpp v41, -v54, v11 row_newbcast:11 row_mask:0xf bank_mask:0xf
	v_fmac_f32_dpp v40, -v54, v12 row_newbcast:12 row_mask:0xf bank_mask:0xf
	v_fmac_f32_dpp v41, -v54, v13 row_newbcast:13 row_mask:0xf bank_mask:0xf
	v_fmac_f32_dpp v40, -v54, v14 row_newbcast:14 row_mask:0xf bank_mask:0xf
	v_fmac_f32_dpp v41, -v54, v15 row_newbcast:15 row_mask:0xf bank_mask:0xf
	v_fmac_f32_dpp v40, -v55, v16 row_newbcast:0 row_mask:0xf bank_mask:0xf
	v_fmac_f32_dpp v41, -v55, v17 row_newbcast:1 row_mask:0xf bank_mask:0xf
	v_fmac_f32_dpp v40, -v55, v18 row_newbcast:2 row_mask:0xf bank_mask:0xf
	v_fmac_f32_dpp v41, -v55, v19 row_newbcast:3 row_mask:0xf bank_mask:0xf
	v_fmac_f32_dpp v40, -v55, v20 row_newbcast:4 row_mask:0xf bank_mask:0xf
	v_fmac_f32_dpp v41, -v55, v21 row_newbcast:5 row_mask:0xf bank_mask:0xf
	v_fmac_f32_dpp v40, -v55, v22 row_newbcast:6 row_mask:0xf bank_mask:0xf
	v_fmac_f32_dpp v41, -v55, v23 row_newbcast:7 row_mask:0xf bank_mask:0xf
	v_fmac_f32_dpp v40, -v55, v24 row_newbcast:8 row_mask:0xf bank_mask:0xf
	v_fmac_f32_dpp v41, -v55, v25 row_newbcast:9 row_mask:0xf bank_mask:0xf
	v_fmac_f32_dpp v40, -v55, v26 row_newbcast:10 row_mask:0xf bank_mask:0xf
	v_fmac_f32_dpp v41, -v55, v27 row_newbcast:11 row_mask:0xf bank_mask:0xf
	v_fmac_f32_dpp v40, -v55, v28 row_newbcast:12 row_mask:0xf bank_mask:0xf
	v_fmac_f32_dpp v41, -v55, v29 row_newbcast:13 row_mask:0xf bank_mask:0xf
	ds_read_b32 v59, v38 offset:64512
	ds_read_b32 v54, v37 offset:16128
	ds_read_b32 v55, v37 offset:16256
	v_add_f32_e32 v42, v40, v41
	v_mov_b32_e32 v43, v42
	s_nop 1
	v_permlane32_swap_b32_e32 v42, v43
	s_nop 1
	v_add_f32_dpp v29, v42, v43 quad_perm:[0,1,2,3] row_mask:0xc bank_mask:0xf
	s_waitcnt lgkmcnt(9)
; #define LAS __attribute__((address_space(3)))
; __device__ __forceinline__ void phase_chunk_prep(const Params& p, LAS unsigned char* lds, int wave_s) {
;     ...
;             for (int i = 0; i < 64; ++i) {
;                 float s0 = RHS[i * 256 + col], s1 = 0.f, s2 = 0.f, s3 = 0.f;
; #pragma unroll
;                 for (int j4 = 0; j4 < (i + 3) / 4; ++j4) { const f32x4 a = *(const LAS f32x4*)(AM + i * 64 + 4 * j4);
;                     s0 -= a.x * sol[4 * j4]; s1 -= a.y * sol[4 * j4 + 1]; s2 -= a.z * sol[4 * j4 + 2]; s3 -= a.w * sol[4 * j4 + 3]; }
;                 sol[i] = (s0 + s1) + (s2 + s3);
;             }
	v_mul_f32_e32 v40, v56, v39
	v_mov_b32_e32 v41, 0
	v_fmac_f32_dpp v40, -v48, v0 row_newbcast:0 row_mask:0xf bank_mask:0xf
	v_fmac_f32_dpp v41, -v48, v1 row_newbcast:1 row_mask:0xf bank_mask:0xf
	v_fmac_f32_dpp v40, -v48, v2 row_newbcast:2 row_mask:0xf bank_mask:0xf
	v_fmac_f32_dpp v41, -v48, v3 row_newbcast:3 row_mask:0xf bank_mask:0xf
	v_fmac_f32_dpp v40, -v48, v4 row_newbcast:4 row_mask:0xf bank_mask:0xf
	v_fmac_f32_dpp v41, -v48, v5 row_newbcast:5 row_mask:0xf bank_mask:0xf
	v_fmac_f32_dpp v40, -v48, v6 row_newbcast:6 row_mask:0xf bank_mask:0xf
	v_fmac_f32_dpp v41, -v48, v7 row_newbcast:7 row_mask:0xf bank_mask:0xf
	v_fmac_f32_dpp v40, -v48, v8 row_newbcast:8 row_mask:0xf bank_mask:0xf
	v_fmac_f32_dpp v41, -v48, v9 row_newbcast:9 row_mask:0xf bank_mask:0xf
	v_fmac_f32_dpp v40, -v48, v10 row_newbcast:10 row_mask:0xf bank_mask:0xf
	v_fmac_f32_dpp v41, -v48, v11 row_newbcast:11 row_mask:0xf bank_mask:0xf
	v_fmac_f32_dpp v40, -v48, v12 row_newbcast:12 row_mask:0xf bank_mask:0xf
	v_fmac_f32_dpp v41, -v48, v13 row_newbcast:13 row_mask:0xf bank_mask:0xf
	v_fmac_f32_dpp v40, -v48, v14 row_newbcast:14 row_mask:0xf bank_mask:0xf
	v_fmac_f32_dpp v41, -v48, v15 row_newbcast:15 row_mask:0xf bank_mask:0xf
	v_fmac_f32_dpp v40, -v49, v16 row_newbcast:0 row_mask:0xf bank_mask:0xf
	v_fmac_f32_dpp v41, -v49, v17 row_newbcast:1 row_mask:0xf bank_mask:0xf
	v_fmac_f32_dpp v40, -v49, v18 row_newbcast:2 row_mask:0xf bank_mask:0xf
	v_fmac_f32_dpp v41, -v49, v19 row_newbcast:3 row_mask:0xf bank_mask:0xf
	v_fmac_f32_dpp v40, -v49, v20 row_newbcast:4 row_mask:0xf bank_mask:0xf
	v_fmac_f32_dpp v41, -v49, v21 row_newbcast:5 row_mask:0xf bank_mask:0xf
	v_fmac_f32_dpp v40, -v49, v22 row_newbcast:6 row_mask:0xf bank_mask:0xf
	v_fmac_f32_dpp v41, -v49, v23 row_newbcast:7 row_mask:0xf bank_mask:0xf
	v_fmac_f32_dpp v40, -v49, v24 row_newbcast:8 row_mask:0xf bank_mask:0xf
	v_fmac_f32_dpp v41, -v49, v25 row_newbcast:9 row_mask:0xf bank_mask:0xf
	v_fmac_f32_dpp v40, -v49, v26 row_newbcast:10 row_mask:0xf bank_mask:0xf
	v_fmac_f32_dpp v41, -v49, v27 row_newbcast:11 row_mask:0xf bank_mask:0xf
	v_fmac_f32_dpp v40, -v49, v28 row_newbcast:12 row_mask:0xf bank_mask:0xf
	v_fmac_f32_dpp v41, -v49, v29 row_newbcast:13 row_mask:0xf bank_mask:0xf
	v_add_f32_e32 v42, v40, v41
	v_mov_b32_e32 v43, v42
	s_nop 1
	v_permlane32_swap_b32_e32 v42, v43
	s_nop 1
	v_add_f32_dpp v30, v42, v43 quad_perm:[0,1,2,3] row_mask:0x3 bank_mask:0xf
	s_waitcnt lgkmcnt(6)
	v_mul_f32_e32 v40, v57, v39
	v_mov_b32_e32 v41, 0
	v_fmac_f32_dpp v40, -v50, v0 row_newbcast:0 row_mask:0xf bank_mask:0xf
	v_fmac_f32_dpp v41, -v50, v1 row_newbcast:1 row_mask:0xf bank_mask:0xf
	v_fmac_f32_dpp v40, -v50, v2 row_newbcast:2 row_mask:0xf bank_mask:0xf
	v_fmac_f32_dpp v41, -v50, v3 row_newbcast:3 row_mask:0xf bank_mask:0xf
	v_fmac_f32_dpp v40, -v50, v4 row_newbcast:4 row_mask:0xf bank_mask:0xf
	v_fmac_f32_dpp v41, -v50, v5 row_newbcast:5 row_mask:0xf bank_mask:0xf
	v_fmac_f32_dpp v40, -v50, v6 row_newbcast:6 row_mask:0xf bank_mask:0xf
	v_fmac_f32_dpp v41, -v50, v7 row_newbcast:7 row_mask:0xf bank_mask:0xf
	v_fmac_f32_dpp v40, -v50, v8 row_newbcast:8 row_mask:0xf bank_mask:0xf
	v_fmac_f32_dpp v41, -v50, v9 row_newbcast:9 row_mask:0xf bank_mask:0xf
	v_fmac_f32_dpp v40, -v50, v10 row_newbcast:10 row_mask:0xf bank_mask:0xf
	v_fmac_f32_dpp v41, -v50, v11 row_newbcast:11 row_mask:0xf bank_mask:0xf
	v_fmac_f32_dpp v40, -v50, v12 row_newbcast:12 row_mask:0xf bank_mask:0xf
	v_fmac_f32_dpp v41, -v50, v13 row_newbcast:13 row_mask:0xf bank_mask:0xf
	v_fmac_f32_dpp v40, -v50, v14 row_newbcast:14 row_mask:0xf bank_mask:0xf
	v_fmac_f32_dpp v41, -v50, v15 row_newbcast:15 row_mask:0xf bank_mask:0xf
	v_fmac_f32_dpp v40, -v51, v16 row_newbcast:0 row_mask:0xf bank_mask:0xf
	v_fmac_f32_dpp v41, -v51, v17 row_newbcast:1 row_mask:0xf bank_mask:0xf
	v_fmac_f32_dpp v40, -v51, v18 row_newbcast:2 row_mask:0xf bank_mask:0xf
	v_fmac_f32_dpp v41, -v51, v19 row_newbcast:3 row_mask:0xf bank_mask:0xf
	v_fmac_f32_dpp v40, -v51, v20 row_newbcast:4 row_mask:0xf bank_mask:0xf
	v_fmac_f32_dpp v41, -v51, v21 row_newbcast:5 row_mask:0xf bank_mask:0xf
	v_fmac_f32_dpp v40, -v51, v22 row_newbcast:6 row_mask:0xf bank_mask:0xf
	v_fmac_f32_dpp v41, -v51, v23 row_newbcast:7 row_mask:0xf bank_mask:0xf
	v_fmac_f32_dpp v40, -v51, v24 row_newbcast:8 row_mask:0xf bank_mask:0xf
	v_fmac_f32_dpp v41, -v51, v25 row_newbcast:9 row_mask:0xf bank_mask:0xf
	v_fmac_f32_dpp v40, -v51, v26 row_newbcast:10 row_mask:0xf bank_mask:0xf
	v_fmac_f32_dpp v41, -v51, v27 row_newbcast:11 row_mask:0xf bank_mask:0xf
	v_fmac_f32_dpp v40, -v51, v28 row_newbcast:12 row_mask:0xf bank_mask:0xf
	v_fmac_f32_dpp v41, -v51, v29 row_newbcast:13 row_mask:0xf bank_mask:0xf
	v_fmac_f32_dpp v40, -v51, v30 row_newbcast:14 row_mask:0xf bank_mask:0xf
	v_add_f32_e32 v42, v40, v41
	v_mov_b32_e32 v43, v42
	s_nop 1
	v_permlane32_swap_b32_e32 v42, v43
	s_nop 1
	v_add_f32_dpp v31, v42, v43 quad_perm:[0,1,2,3] row_mask:0x3 bank_mask:0xf
	s_waitcnt lgkmcnt(3)
; #define LAS __attribute__((address_space(3)))
; __device__ __forceinline__ void phase_chunk_prep(const Params& p, LAS unsigned char* lds, int wave_s) {
;     ...
;             for (int i = 0; i < 64; ++i) {
;                 float s0 = RHS[i * 256 + col], s1 = 0.f, s2 = 0.f, s3 = 0.f;
; #pragma unroll
;                 for (int j4 = 0; j4 < (i + 3) / 4; ++j4) { const f32x4 a = *(const LAS f32x4*)(AM + i * 64 + 4 * j4);
;                     s0 -= a.x * sol[4 * j4]; s1 -= a.y * sol[4 * j4 + 1]; s2 -= a.z * sol[4 * j4 + 2]; s3 -= a.w * sol[4 * j4 + 3]; }
;                 sol[i] = (s0 + s1) + (s2 + s3);
;             }
;             if (col < 128) {
; #pragma unroll
;                 for (int mm = 0; mm < 4; ++mm)
; #pragma unroll
;                     for (int q4 = 0; q4 < 4; ++q4)
;                         *(f32x4*)(U + ((((col >> 4) * 4 + mm) * 64 + q4 * 16 + (col & 15)) << 2)) = (f32x4){sol[16 * mm + 4 * q4], sol[16 * mm + 4 * q4 + 1], sol[16 * mm + 4 * q4 + 2], sol[16 * mm + 4 * q4 + 3]};
	v_mul_f32_e32 v40, v58, v39
	v_mov_b32_e32 v41, 0
	v_fmac_f32_dpp v40, -v52, v0 row_newbcast:0 row_mask:0xf bank_mask:0xf
	v_fmac_f32_dpp v41, -v52, v1 row_newbcast:1 row_mask:0xf bank_mask:0xf
	v_fmac_f32_dpp v40, -v52, v2 row_newbcast:2 row_mask:0xf bank_mask:0xf
	v_fmac_f32_dpp v41, -v52, v3 row_newbcast:3 row_mask:0xf bank_mask:0xf
	v_fmac_f32_dpp v40, -v52, v4 row_newbcast:4 row_mask:0xf bank_mask:0xf
	v_fmac_f32_dpp v41, -v52, v5 row_newbcast:5 row_mask:0xf bank_mask:0xf
	v_fmac_f32_dpp v40, -v52, v6 row_newbcast:6 row_mask:0xf bank_mask:0xf
	v_fmac_f32_dpp v41, -v52, v7 row_newbcast:7 row_mask:0xf bank_mask:0xf
	v_fmac_f32_dpp v40, -v52, v8 row_newbcast:8 row_mask:0xf bank_mask:0xf
	v_fmac_f32_dpp v41, -v52, v9 row_newbcast:9 row_mask:0xf bank_mask:0xf
	v_fmac_f32_dpp v40, -v52, v10 row_newbcast:10 row_mask:0xf bank_mask:0xf
	v_fmac_f32_dpp v41, -v52, v11 row_newbcast:11 row_mask:0xf bank_mask:0xf
	v_fmac_f32_dpp v40, -v52, v12 row_newbcast:12 row_mask:0xf bank_mask:0xf
	v_fmac_f32_dpp v41, -v52, v13 row_newbcast:13 row_mask:0xf bank_mask:0xf
	v_fmac_f32_dpp v40, -v52, v14 row_newbcast:14 row_mask:0xf bank_mask:0xf
	v_fmac_f32_dpp v41, -v52, v15 row_newbcast:15 row_mask:0xf bank_mask:0xf
	v_fmac_f32_dpp v40, -v53, v16 row_newbcast:0 row_mask:0xf bank_mask:0xf
	v_fmac_f32_dpp v41, -v53, v17 row_newbcast:1 row_mask:0xf bank_mask:0xf
	v_fmac_f32_dpp v40, -v53, v18 row_newbcast:2 row_mask:0xf bank_mask:0xf
	v_fmac_f32_dpp v41, -v53, v19 row_newbcast:3 row_mask:0xf bank_mask:0xf
	v_fmac_f32_dpp v40, -v53, v20 row_newbcast:4 row_mask:0xf bank_mask:0xf
	v_fmac_f32_dpp v41, -v53, v21 row_newbcast:5 row_mask:0xf bank_mask:0xf
	v_fmac_f32_dpp v40, -v53, v22 row_newbcast:6 row_mask:0xf bank_mask:0xf
	v_fmac_f32_dpp v41, -v53, v23 row_newbcast:7 row_mask:0xf bank_mask:0xf
	v_fmac_f32_dpp v40, -v53, v24 row_newbcast:8 row_mask:0xf bank_mask:0xf
	v_fmac_f32_dpp v41, -v53, v25 row_newbcast:9 row_mask:0xf bank_mask:0xf
	v_fmac_f32_dpp v40, -v53, v26 row_newbcast:10 row_mask:0xf bank_mask:0xf
	v_fmac_f32_dpp v41, -v53, v27 row_newbcast:11 row_mask:0xf bank_mask:0xf
	v_fmac_f32_dpp v40, -v53, v28 row_newbcast:12 row_mask:0xf bank_mask:0xf
	v_fmac_f32_dpp v41, -v53, v29 row_newbcast:13 row_mask:0xf bank_mask:0xf
	v_fmac_f32_dpp v40, -v53, v30 row_newbcast:14 row_mask:0xf bank_mask:0xf
	v_fmac_f32_dpp v41, -v53, v31 row_newbcast:15 row_mask:0xf bank_mask:0xf
	v_add_f32_e32 v42, v40, v41
	v_mov_b32_e32 v43, v42
	s_nop 1
	v_permlane32_swap_b32_e32 v42, v43
	s_nop 1
	v_add_f32_dpp v30, v42, v43 quad_perm:[0,1,2,3] row_mask:0xc bank_mask:0xf
	s_waitcnt lgkmcnt(0)
	v_mul_f32_e32 v40, v59, v39
	v_mov_b32_e32 v41, 0
	v_fmac_f32_dpp v40, -v54, v0 row_newbcast:0 row_mask:0xf bank_mask:0xf
	v_fmac_f32_dpp v41, -v54, v1 row_newbcast:1 row_mask:0xf bank_mask:0xf
	v_fmac_f32_dpp v40, -v54, v2 row_newbcast:2 row_mask:0xf bank_mask:0xf
	v_fmac_f32_dpp v41, -v54, v3 row_newbcast:3 row_mask:0xf bank_mask:0xf
	v_fmac_f32_dpp v40, -v54, v4 row_newbcast:4 row_mask:0xf bank_mask:0xf
	v_fmac_f32_dpp v41, -v54, v5 row_newbcast:5 row_mask:0xf bank_mask:0xf
	v_fmac_f32_dpp v40, -v54, v6 row_newbcast:6 row_mask:0xf bank_mask:0xf
	v_fmac_f32_dpp v41, -v54, v7 row_newbcast:7 row_mask:0xf bank_mask:0xf
	v_fmac_f32_dpp v40, -v54, v8 row_newbcast:8 row_mask:0xf bank_mask:0xf
	v_fmac_f32_dpp v41, -v54, v9 row_newbcast:9 row_mask:0xf bank_mask:0xf
	v_fmac_f32_dpp v40, -v54, v10 row_newbcast:10 row_mask:0xf bank_mask:0xf
	v_fmac_f32_dpp v41, -v54, v11 row_newbcast:11 row_mask:0xf bank_mask:0xf
	v_fmac_f32_dpp v40, -v54, v12 row_newbcast:12 row_mask:0xf bank_mask:0xf
	v_fmac_f32_dpp v41, -v54, v13 row_newbcast:13 row_mask:0xf bank_mask:0xf
	v_fmac_f32_dpp v40, -v54, v14 row_newbcast:14 row_mask:0xf bank_mask:0xf
	v_fmac_f32_dpp v41, -v54, v15 row_newbcast:15 row_mask:0xf bank_mask:0xf
	v_fmac_f32_dpp v40, -v55, v16 row_newbcast:0 row_mask:0xf bank_mask:0xf
	v_fmac_f32_dpp v41, -v55, v17 row_newbcast:1 row_mask:0xf bank_mask:0xf
	v_fmac_f32_dpp v40, -v55, v18 row_newbcast:2 row_mask:0xf bank_mask:0xf
	v_fmac_f32_dpp v41, -v55, v19 row_newbcast:3 row_mask:0xf bank_mask:0xf
	v_fmac_f32_dpp v40, -v55, v20 row_newbcast:4 row_mask:0xf bank_mask:0xf
	v_fmac_f32_dpp v41, -v55, v21 row_newbcast:5 row_mask:0xf bank_mask:0xf
	v_fmac_f32_dpp v40, -v55, v22 row_newbcast:6 row_mask:0xf bank_mask:0xf
	v_fmac_f32_dpp v41, -v55, v23 row_newbcast:7 row_mask:0xf bank_mask:0xf
	v_fmac_f32_dpp v40, -v55, v24 row_newbcast:8 row_mask:0xf bank_mask:0xf
	v_fmac_f32_dpp v41, -v55, v25 row_newbcast:9 row_mask:0xf bank_mask:0xf
	v_fmac_f32_dpp v40, -v55, v26 row_newbcast:10 row_mask:0xf bank_mask:0xf
	v_fmac_f32_dpp v41, -v55, v27 row_newbcast:11 row_mask:0xf bank_mask:0xf
	v_fmac_f32_dpp v40, -v55, v28 row_newbcast:12 row_mask:0xf bank_mask:0xf
	v_fmac_f32_dpp v41, -v55, v29 row_newbcast:13 row_mask:0xf bank_mask:0xf
	v_fmac_f32_dpp v40, -v55, v30 row_newbcast:14 row_mask:0xf bank_mask:0xf
	v_fmac_f32_dpp v41, -v55, v31 row_newbcast:15 row_mask:0xf bank_mask:0xf
	v_add_f32_e32 v42, v40, v41
	v_mov_b32_e32 v43, v42
	s_nop 1
	v_permlane32_swap_b32_e32 v42, v43
	s_nop 1
	v_add_f32_dpp v31, v42, v43 quad_perm:[0,1,2,3] row_mask:0xc bank_mask:0xf
	s_cmp_gt_u32 s84, 3
	s_cbranch_scc1 .Lfsub_wdec
	s_lshl_b32 s96, s16, 15
	s_add_u32 s96, s20, s96
	s_addc_u32 s97, s21, 0
	v_lshrrev_b32_e32 v72, 4, v35
	v_lshlrev_b32_e32 v72, 12, v72
	v_and_b32_e32 v73, 15, v35
	v_lshl_add_u32 v72, v73, 4, v72
	v_lshl_add_u32 v72, v34, 3, v72
	global_store_dwordx2 v72, v[0:1], s[96:97]
	global_store_dwordx2 v72, v[2:3], s[96:97] offset:256
	global_store_dwordx2 v72, v[4:5], s[96:97] offset:512
	global_store_dwordx2 v72, v[6:7], s[96:97] offset:768
	global_store_dwordx2 v72, v[8:9], s[96:97] offset:1024
	global_store_dwordx2 v72, v[10:11], s[96:97] offset:1280
	global_store_dwordx2 v72, v[12:13], s[96:97] offset:1536
	global_store_dwordx2 v72, v[14:15], s[96:97] offset:1792
	global_store_dwordx2 v72, v[16:17], s[96:97] offset:2048
	global_store_dwordx2 v72, v[18:19], s[96:97] offset:2304
	global_store_dwordx2 v72, v[20:21], s[96:97] offset:2560
	global_store_dwordx2 v72, v[22:23], s[96:97] offset:2816
	global_store_dwordx2 v72, v[24:25], s[96:97] offset:3072
	global_store_dwordx2 v72, v[26:27], s[96:97] offset:3328
	global_store_dwordx2 v72, v[28:29], s[96:97] offset:3584
	global_store_dwordx2 v72, v[30:31], s[96:97] offset:3840
	s_waitcnt vmcnt(16)
	s_branch .LBB0_663
; __device__ __forceinline__ bf16_t f2bf(float x) { return (bf16_t)(pk2(x, 0.f) & 0xffffu); }
; __device__ __forceinline__ void phase_chunk_prep(const Params& p, LAS unsigned char* lds, int wave_s) {
;     ...
;             } else {
; #pragma unroll
;                 for (int i = 0; i < 64; ++i) img[IMG_WD + i * SWD + (col - 128)] = f2bf(sol[i]);
;             }
.Lfsub_wdec:
	v_add_u32_e32 v72, 0xffffff80, v35
	v_lshlrev_b32_e32 v72, 1, v72
	v_mul_u32_u24_e32 v73, 0x210, v34
	v_add_u32_e32 v72, v72, v73
	s_mov_b64 s[96:97], s[30:31]
	v_cvt_pk_bf16_f32 v74, v0, v0
	global_store_short v72, v74, s[96:97]
	v_cvt_pk_bf16_f32 v74, v1, v1
	global_store_short v72, v74, s[96:97] offset:264
	v_cvt_pk_bf16_f32 v74, v2, v2
	global_store_short v72, v74, s[96:97] offset:1056
	v_cvt_pk_bf16_f32 v74, v3, v3
	global_store_short v72, v74, s[96:97] offset:1320
	v_cvt_pk_bf16_f32 v74, v4, v4
	global_store_short v72, v74, s[96:97] offset:2112
	v_cvt_pk_bf16_f32 v74, v5, v5
	global_store_short v72, v74, s[96:97] offset:2376
	v_cvt_pk_bf16_f32 v74, v6, v6
	global_store_short v72, v74, s[96:97] offset:3168
	v_cvt_pk_bf16_f32 v74, v7, v7
	global_store_short v72, v74, s[96:97] offset:3432
	s_add_u32 s96, s96, 0x1080
	s_addc_u32 s97, s97, 0
	v_cvt_pk_bf16_f32 v74, v8, v8
	global_store_short v72, v74, s[96:97]
	v_cvt_pk_bf16_f32 v74, v9, v9
	global_store_short v72, v74, s[96:97] offset:264
	v_cvt_pk_bf16_f32 v74, v10, v10
	global_store_short v72, v74, s[96:97] offset:1056
	v_cvt_pk_bf16_f32 v74, v11, v11
	global_store_short v72, v74, s[96:97] offset:1320
	v_cvt_pk_bf16_f32 v74, v12, v12
	global_store_short v72, v74, s[96:97] offset:2112
	v_cvt_pk_bf16_f32 v74, v13, v13
	global_store_short v72, v74, s[96:97] offset:2376
	v_cvt_pk_bf16_f32 v74, v14, v14
	global_store_short v72, v74, s[96:97] offset:3168
	v_cvt_pk_bf16_f32 v74, v15, v15
	global_store_short v72, v74, s[96:97] offset:3432
	s_add_u32 s96, s96, 0x1080
	s_addc_u32 s97, s97, 0
	v_cvt_pk_bf16_f32 v74, v16, v16
	global_store_short v72, v74, s[96:97]
	v_cvt_pk_bf16_f32 v74, v17, v17
	global_store_short v72, v74, s[96:97] offset:264
	v_cvt_pk_bf16_f32 v74, v18, v18
	global_store_short v72, v74, s[96:97] offset:1056
	v_cvt_pk_bf16_f32 v74, v19, v19
	global_store_short v72, v74, s[96:97] offset:1320
	v_cvt_pk_bf16_f32 v74, v20, v20
	global_store_short v72, v74, s[96:97] offset:2112
	v_cvt_pk_bf16_f32 v74, v21, v21
	global_store_short v72, v74, s[96:97] offset:2376
	v_cvt_pk_bf16_f32 v74, v22, v22
	global_store_short v72, v74, s[96:97] offset:3168
	v_cvt_pk_bf16_f32 v74, v23, v23
	global_store_short v72, v74, s[96:97] offset:3432
	s_add_u32 s96, s96, 0x1080
	s_addc_u32 s97, s97, 0
	v_cvt_pk_bf16_f32 v74, v24, v24
	global_store_short v72, v74, s[96:97]
	v_cvt_pk_bf16_f32 v74, v25, v25
	global_store_short v72, v74, s[96:97] offset:264
	v_cvt_pk_bf16_f32 v74, v26, v26
	global_store_short v72, v74, s[96:97] offset:1056
	v_cvt_pk_bf16_f32 v74, v27, v27
	global_store_short v72, v74, s[96:97] offset:1320
	v_cvt_pk_bf16_f32 v74, v28, v28
	global_store_short v72, v74, s[96:97] offset:2112
	v_cvt_pk_bf16_f32 v74, v29, v29
	global_store_short v72, v74, s[96:97] offset:2376
	v_cvt_pk_bf16_f32 v74, v30, v30
	global_store_short v72, v74, s[96:97] offset:3168
	v_cvt_pk_bf16_f32 v74, v31, v31
	global_store_short v72, v74, s[96:97] offset:3432
	s_waitcnt vmcnt(32)
	s_branch .LBB0_663
